# retention increment / scan units: per-head decay parameter fetched with scalar loads (lane-uniform read-only input) instead of vector loads
# baseline (speedup 1.0000x reference)
.LBB0_646:
	s_andn2_b64 vcc, exec, s[6:7]
	s_mov_b32 s94, s18
	s_cbranch_vccnz .LBB0_648
	s_lshl_b32 s6, s12, 1
	s_add_i32 s0, s6, 0xfbe0
	s_and_b32 s7, s0, 0xfffe
	s_mul_i32 s7, s7, 0xf0f1
	s_lshr_b32 s7, s7, 21
	s_mul_i32 s7, s7, 34
	s_sub_i32 s0, s0, s7
	s_and_b32 s0, s0, 0xfffe
	s_lshl_b32 s7, s0, 7
	s_cmp_eq_u32 s0, 0
	s_movk_i32 s16, 0xff00
	s_movk_i32 s17, 0x300
	s_cselect_b32 s8, 0x4000, s16
	s_cselect_b32 s9, s17, 0x3000
	s_add_i32 s6, s6, 0xfbe1
	s_add_i32 s13, s8, s7
	s_and_b32 s7, s6, 0xffff
	s_mul_i32 s7, s7, 0xf0f1
	s_lshr_b32 s7, s7, 21
	s_mul_i32 s7, s7, 34
	s_sub_i32 s6, s6, s7
	s_and_b32 s8, s6, 0xffff
	s_add_i32 s13, s13, s9
	s_lshl_b32 s6, s8, 7
	s_cmp_eq_u32 s8, 1
	s_cselect_b32 s7, 0x4000, s16
	s_cselect_b32 s9, s17, 0x3000
	s_add_i32 s6, s7, s6
	s_add_i32 s9, s6, s9
	s_lshl_b32 s6, s5, 3
	s_ashr_i32 s7, s6, 31
	s_lshl_b64 s[6:7], s[6:7], 2
	s_add_u32 s6, s42, s6
	s_addc_u32 s7, s43, s7
	s_load_dword s100, s[6:7], 0xc
	s_load_dword s101, s[6:7], 0x1c
	s_mov_b32 s6, 0xbfb8aa3b
	s_mov_b32 s16, 0x3f317218
	s_mov_b32 s7, 0x7f800000
	s_mov_b32 s17, 0x33800000
	v_ashrrev_i32_e32 v31, 3, v206
	v_readlane_b32 s20, v254, 56
	v_readlane_b32 s21, v254, 57
	v_and_b32_e32 v16, 15, v206
	v_lshlrev_b32_e32 v102, 2, v16
	v_and_b32_e32 v86, 12, v102
	v_mov_b32_e32 v62, 0x1400
	v_mov_b32_e32 v80, 0x1e00
	s_mov_b32 s94, 2
	s_waitcnt lgkmcnt(0)
	v_mov_b32_e32 v0, s100
	v_mov_b32_e32 v1, s101
	v_mul_f32_e32 v2, 0xbfb8aa3b, v0
	v_mul_f32_e32 v3, 0xbfb8aa3b, v1
	v_fma_f32 v4, v0, s6, -v2
	v_rndne_f32_e32 v5, v2
	v_fma_f32 v6, v1, s6, -v3
	v_rndne_f32_e32 v7, v3
	v_fmac_f32_e32 v4, 0xb2a5705f, v0
	v_sub_f32_e32 v2, v2, v5
	v_fmac_f32_e32 v6, 0xb2a5705f, v1
	v_sub_f32_e32 v3, v3, v7
	v_add_f32_e32 v2, v2, v4
	v_cvt_i32_f32_e32 v5, v5
	v_add_f32_e32 v3, v3, v6
	v_exp_f32_e32 v2, v2
	v_cvt_i32_f32_e32 v7, v7
	v_exp_f32_e32 v3, v3
	s_mov_b32 s6, 0x42ce8ed0
	v_ldexp_f32 v2, v2, v5
	v_cmp_nlt_f32_e32 vcc, s6, v0
	v_ldexp_f32 v3, v3, v7
	s_nop 0
	v_cndmask_b32_e32 v2, 0, v2, vcc
	v_cmp_nlt_f32_e32 vcc, s6, v1
	s_mov_b32 s6, 0xc2b17218
	s_nop 0
	v_cndmask_b32_e32 v3, 0, v3, vcc
	v_cmp_ngt_f32_e32 vcc, s6, v0
	s_nop 1
	v_cndmask_b32_e32 v17, v227, v2, vcc
	v_cmp_ngt_f32_e32 vcc, s6, v1
	v_add_f32_e32 v1, 1.0, v17
	v_frexp_mant_f32_e32 v7, v1
	v_cndmask_b32_e32 v0, v227, v3, vcc
	v_cvt_f64_f32_e32 v[2:3], v1
	s_mov_b32 s6, 0x3f2aaaab
	v_add_f32_e32 v20, 1.0, v0
	v_add_f32_e32 v6, -1.0, v1
	v_frexp_exp_i32_f64_e32 v2, v[2:3]
	v_cmp_gt_f32_e32 vcc, s6, v7
	v_add_f32_e32 v8, -1.0, v20
	v_cvt_f64_f32_e32 v[4:5], v20
	v_sub_f32_e32 v9, v6, v1
	v_subbrev_co_u32_e32 v2, vcc, 0, v2, vcc
	v_sub_f32_e32 v6, v17, v6
	v_sub_f32_e32 v3, v8, v20
	v_frexp_exp_i32_f64_e32 v22, v[4:5]
	v_add_f32_e32 v4, 1.0, v9
	v_sub_u32_e32 v5, 0, v2
	v_sub_f32_e32 v8, v0, v8
	v_add_f32_e32 v3, 1.0, v3
	v_add_f32_e32 v4, v6, v4
	v_ldexp_f32 v1, v1, v5
	v_add_f32_e32 v23, v8, v3
	v_ldexp_f32 v3, v4, v5
	v_add_f32_e32 v4, -1.0, v1
	v_add_f32_e32 v6, 1.0, v1
	v_add_f32_e32 v5, 1.0, v4
	v_add_f32_e32 v7, -1.0, v6
	v_sub_f32_e32 v5, v1, v5
	v_sub_f32_e32 v1, v1, v7
	v_add_f32_e32 v1, v3, v1
	v_add_f32_e32 v7, v3, v5
	v_add_f32_e32 v3, v6, v1
	v_rcp_f32_e32 v10, v3
	v_add_f32_e32 v5, v4, v7
	v_sub_f32_e32 v6, v6, v3
	v_add_f32_e32 v1, v1, v6
	v_mul_f32_e32 v12, v5, v10
	v_mul_f32_e32 v6, v3, v12
	v_fma_f32 v8, v12, v3, -v6
	v_sub_f32_e32 v4, v4, v5
	v_fmac_f32_e32 v8, v12, v1
	v_add_f32_e32 v11, v7, v4
	v_add_f32_e32 v4, v6, v8
	v_sub_f32_e32 v7, v5, v4
	v_mov_b32_e32 v9, v4
	v_pk_add_f32 v[4:5], v[4:5], v[6:7] neg_lo:[0,1] neg_hi:[0,1]
	v_cvt_f32_i32_e32 v2, v2
	v_pk_add_f32 v[4:5], v[4:5], v[8:9] neg_lo:[0,1] neg_hi:[0,1]
	v_cmp_neq_f32_e32 vcc, s7, v17
	v_add_f32_e32 v5, v11, v5
	v_add_f32_e32 v4, v4, v5
	v_add_f32_e32 v5, v7, v4
	v_mul_f32_e32 v9, v10, v5
	v_mul_f32_e32 v6, v3, v9
	v_fma_f32 v8, v9, v3, -v6
	v_sub_f32_e32 v7, v7, v5
	v_fmac_f32_e32 v8, v9, v1
	v_add_f32_e32 v11, v4, v7
	v_add_f32_e32 v13, v12, v9
	v_add_f32_e32 v4, v6, v8
	v_sub_f32_e32 v3, v13, v12
	v_sub_f32_e32 v7, v5, v4
	v_sub_f32_e32 v1, v9, v3
	v_mov_b32_e32 v9, v4
	v_pk_add_f32 v[4:5], v[4:5], v[6:7] neg_lo:[0,1] neg_hi:[0,1]
	v_frexp_mant_f32_e32 v21, v20
	v_pk_add_f32 v[4:5], v[4:5], v[8:9] neg_lo:[0,1] neg_hi:[0,1]
	s_nop 0
	v_add_f32_e32 v3, v11, v5
	v_add_f32_e32 v3, v4, v3
	v_add_f32_e32 v3, v7, v3
	v_mul_f32_e32 v3, v10, v3
	v_add_f32_e32 v1, v1, v3
	v_add_f32_e32 v3, v13, v1
	v_mul_f32_e32 v4, v3, v3
	v_fmamk_f32 v7, v4, 0x3e9b6dac, v252
	v_sub_f32_e32 v6, v3, v13
	v_ldexp_f32 v5, v3, 1
	v_mul_f32_e32 v3, v3, v4
	v_fmaak_f32 v201, v4, v7, 0x3f2aaada
	v_sub_f32_e32 v1, v1, v6
	v_pk_mul_f32 v[6:7], v[2:3], v[200:201]
	v_ldexp_f32 v1, v1, 1
	v_fma_f32 v4, v2, s16, -v6
	v_fmac_f32_e32 v4, 0xb102e308, v2
	v_pk_add_f32 v[2:3], v[6:7], v[4:5]
	v_mov_b32_e32 v8, v6
	v_sub_f32_e32 v9, v3, v5
	v_pk_add_f32 v[10:11], v[2:3], v[6:7] neg_lo:[0,1] neg_hi:[0,1]
	v_sub_f32_e32 v7, v7, v9
	v_add_f32_e32 v9, v1, v7
	v_pk_add_f32 v[14:15], v[2:3], v[8:9]
	v_mov_b32_e32 v5, v2
	v_mov_b32_e32 v11, v15
	v_pk_add_f32 v[18:19], v[4:5], v[10:11] neg_lo:[0,1] neg_hi:[0,1]
	v_pk_add_f32 v[4:5], v[4:5], v[10:11]
	v_mov_b32_e32 v6, v3
	v_mov_b32_e32 v13, v2
	v_pk_add_f32 v[2:3], v[4:5], v[2:3] op_sel:[1,0] op_sel_hi:[0,1] neg_lo:[0,1] neg_hi:[0,1]
	v_mov_b32_e32 v12, v9
	v_mov_b32_e32 v8, v15
	v_mov_b32_e32 v9, v5
	v_mov_b32_e32 v7, v2
	v_pk_add_f32 v[10:11], v[14:15], v[2:3] op_sel_hi:[1,0] neg_lo:[0,1] neg_hi:[0,1]
	v_pk_add_f32 v[2:3], v[8:9], v[6:7] neg_lo:[0,1] neg_hi:[0,1]
	v_mov_b32_e32 v10, v18
	v_pk_add_f32 v[2:3], v[12:13], v[2:3] neg_lo:[0,1] neg_hi:[0,1]
	v_mov_b32_e32 v19, v5
	v_pk_add_f32 v[6:7], v[10:11], v[2:3]
	s_nop 0
	v_pk_add_f32 v[8:9], v[6:7], v[6:7] op_sel:[0,1] op_sel_hi:[1,0]
	s_nop 0
	v_pk_add_f32 v[4:5], v[4:5], v[8:9] op_sel:[1,0] op_sel_hi:[0,1]
	v_mov_b32_e32 v7, v4
	v_mov_b32_e32 v3, v8
	v_pk_add_f32 v[8:9], v[6:7], v[18:19] neg_lo:[0,1] neg_hi:[0,1]
	s_nop 0
	v_sub_f32_e32 v1, v6, v8
	v_pk_add_f32 v[2:3], v[2:3], v[8:9] neg_lo:[0,1] neg_hi:[0,1]
	v_sub_f32_e32 v1, v18, v1
	v_add_f32_e32 v1, v2, v1
	v_add_f32_e32 v1, v1, v3
	v_add_f32_e32 v1, v4, v1
	v_cndmask_b32_e32 v1, v227, v1, vcc
	v_cmp_lt_f32_e64 vcc, |v17|, s17
	s_nop 1
	v_cndmask_b32_e32 v17, v1, v17, vcc
	v_cmp_gt_f32_e32 vcc, s6, v21
	s_movk_i32 s6, 0x1000
	s_nop 0
	v_subbrev_co_u32_e32 v1, vcc, 0, v22, vcc
	v_sub_u32_e32 v2, 0, v1
	v_ldexp_f32 v3, v20, v2
	v_add_f32_e32 v4, -1.0, v3
	v_add_f32_e32 v6, 1.0, v3
	v_add_f32_e32 v5, 1.0, v4
	v_add_f32_e32 v7, -1.0, v6
	v_ldexp_f32 v2, v23, v2
	v_sub_f32_e32 v5, v3, v5
	v_sub_f32_e32 v3, v3, v7
	v_add_f32_e32 v5, v2, v5
	v_add_f32_e32 v2, v2, v3
	v_add_f32_e32 v10, v6, v2
	v_rcp_f32_e32 v12, v10
	v_sub_f32_e32 v3, v6, v10
	v_add_f32_e32 v11, v2, v3
	v_add_f32_e32 v3, v4, v5
	v_mul_f32_e32 v14, v3, v12
	v_sub_f32_e32 v2, v4, v3
	v_mul_f32_e32 v4, v10, v14
	v_fma_f32 v6, v14, v10, -v4
	v_fmac_f32_e32 v6, v14, v11
	v_add_f32_e32 v13, v5, v2
	v_add_f32_e32 v2, v4, v6
	v_sub_f32_e32 v5, v3, v2
	v_pk_add_f32 v[8:9], v[2:3], v[4:5] neg_lo:[0,1] neg_hi:[0,1]
	v_mov_b32_e32 v7, v2
	v_pk_add_f32 v[2:3], v[8:9], v[6:7] neg_lo:[0,1] neg_hi:[0,1]
	s_nop 0
	v_add_f32_e32 v3, v13, v3
	v_add_f32_e32 v2, v2, v3
	v_add_f32_e32 v3, v5, v2
	v_mul_f32_e32 v13, v12, v3
	v_mul_f32_e32 v4, v10, v13
	v_fma_f32 v6, v13, v10, -v4
	v_fmac_f32_e32 v6, v13, v11
	v_sub_f32_e32 v5, v5, v3
	v_add_f32_e32 v10, v2, v5
	v_add_f32_e32 v2, v4, v6
	v_sub_f32_e32 v5, v3, v2
	v_pk_add_f32 v[8:9], v[2:3], v[4:5] neg_lo:[0,1] neg_hi:[0,1]
	v_mov_b32_e32 v7, v2
	v_pk_add_f32 v[2:3], v[8:9], v[6:7] neg_lo:[0,1] neg_hi:[0,1]
	s_nop 0
	v_add_f32_e32 v3, v10, v3
	v_add_f32_e32 v2, v2, v3
	v_add_f32_e32 v3, v14, v13
	v_add_f32_e32 v2, v5, v2
	v_sub_f32_e32 v4, v3, v14
	v_mul_f32_e32 v2, v12, v2
	v_sub_f32_e32 v4, v13, v4
	v_add_f32_e32 v4, v4, v2
	v_add_f32_e32 v6, v3, v4
	v_mul_f32_e32 v7, v6, v6
	v_fmamk_f32 v2, v7, 0x3e9b6dac, v252
	v_fmaak_f32 v201, v7, v2, 0x3f2aaada
	v_cvt_f32_i32_e32 v2, v1
	v_sub_f32_e32 v1, v6, v3
	v_mul_f32_e32 v3, v6, v7
	v_ldexp_f32 v5, v6, 1
	v_pk_mul_f32 v[6:7], v[2:3], v[200:201]
	v_sub_f32_e32 v1, v4, v1
	v_fma_f32 v4, v2, s16, -v6
	v_fmac_f32_e32 v4, 0xb102e308, v2
	v_pk_add_f32 v[2:3], v[6:7], v[4:5]
	v_ldexp_f32 v1, v1, 1
	v_sub_f32_e32 v5, v3, v5
	v_sub_f32_e32 v5, v7, v5
	v_add_f32_e32 v9, v1, v5
	v_lshlrev_b32_e32 v1, 3, v206
	v_and_b32_e32 v30, 56, v1
	v_add_u32_e32 v12, s13, v31
	v_mov_b32_e32 v8, v6
	v_lshlrev_b32_e32 v32, 1, v30
	v_ashrrev_i32_e32 v13, 31, v12
	v_pk_add_f32 v[6:7], v[2:3], v[6:7] neg_lo:[0,1] neg_hi:[0,1]
	v_pk_add_f32 v[10:11], v[2:3], v[8:9]
	v_lshl_add_u64 v[34:35], s[20:21], 0, v[32:33]
	v_lshlrev_b64 v[12:13], 13, v[12:13]
	v_lshl_add_u64 v[12:13], v[34:35], 0, v[12:13]
	v_mov_b32_e32 v7, v11
	v_mov_b32_e32 v5, v2
	v_add_co_u32_e32 v12, vcc, s6, v12
	v_pk_add_f32 v[14:15], v[4:5], v[6:7] neg_lo:[0,1] neg_hi:[0,1]
	v_pk_add_f32 v[4:5], v[4:5], v[6:7]
	v_addc_co_u32_e32 v13, vcc, 0, v13, vcc
	v_pk_add_f32 v[6:7], v[4:5], v[2:3] op_sel:[1,0] op_sel_hi:[0,1] neg_lo:[0,1] neg_hi:[0,1]
	global_load_dwordx4 v[18:21], v[12:13], off offset:1024
	v_pk_add_f32 v[22:23], v[10:11], v[6:7] op_sel_hi:[1,0] neg_lo:[0,1] neg_hi:[0,1]
	v_mov_b32_e32 v10, v11
	v_mov_b32_e32 v11, v5
	v_mov_b32_e32 v24, v3
	v_mov_b32_e32 v25, v6
	v_pk_add_f32 v[6:7], v[10:11], v[24:25] neg_lo:[0,1] neg_hi:[0,1]
	v_mov_b32_e32 v8, v9
	v_mov_b32_e32 v9, v2
	v_pk_add_f32 v[2:3], v[8:9], v[6:7] neg_lo:[0,1] neg_hi:[0,1]
	v_mov_b32_e32 v22, v14
	v_pk_add_f32 v[6:7], v[22:23], v[2:3]
	v_mov_b32_e32 v15, v5
	v_pk_add_f32 v[8:9], v[6:7], v[6:7] op_sel:[0,1] op_sel_hi:[1,0]
	v_cmp_neq_f32_e32 vcc, s7, v0
	v_pk_add_f32 v[4:5], v[4:5], v[8:9] op_sel:[1,0] op_sel_hi:[0,1]
	v_mov_b32_e32 v7, v4
	v_pk_add_f32 v[10:11], v[6:7], v[14:15] neg_lo:[0,1] neg_hi:[0,1]
	v_mov_b32_e32 v3, v8
	v_sub_f32_e32 v1, v6, v10
	v_pk_add_f32 v[2:3], v[2:3], v[10:11] neg_lo:[0,1] neg_hi:[0,1]
	v_sub_f32_e32 v1, v14, v1
	v_add_f32_e32 v1, v2, v1
	v_add_f32_e32 v1, v1, v3
	v_add_f32_e32 v1, v4, v1
	v_cndmask_b32_e32 v1, v227, v1, vcc
	v_cmp_lt_f32_e64 vcc, |v0|, s17
	global_load_dwordx4 v[22:25], v[12:13], off offset:1536
	v_cndmask_b32_e32 v32, v1, v0, vcc
	v_add_u32_e32 v0, 0x200, v206
	v_ashrrev_i32_e32 v37, 3, v0
	v_add_u32_e32 v0, s13, v37
	v_ashrrev_i32_e32 v1, 31, v0
	v_lshlrev_b64 v[0:1], 13, v[0:1]
	v_lshl_add_u64 v[0:1], v[34:35], 0, v[0:1]
	v_add_co_u32_e32 v0, vcc, s6, v0
	s_nop 0
	v_addc_co_u32_e32 v1, vcc, 0, v1, vcc
	global_load_dwordx4 v[26:29], v[0:1], off offset:1024
	global_load_dwordx4 v[38:41], v[0:1], off offset:1536
	v_add_u32_e32 v0, s9, v31
	v_ashrrev_i32_e32 v1, 31, v0
	v_lshlrev_b64 v[0:1], 13, v[0:1]
	v_lshl_add_u64 v[0:1], v[34:35], 0, v[0:1]
	v_add_co_u32_e32 v0, vcc, s6, v0
	s_nop 0
	v_addc_co_u32_e32 v1, vcc, 0, v1, vcc
	global_load_dwordx4 v[12:15], v[0:1], off offset:1024
	global_load_dwordx4 v[8:11], v[0:1], off offset:1536
	v_add_u32_e32 v0, s9, v37
	v_ashrrev_i32_e32 v1, 31, v0
	v_lshlrev_b64 v[0:1], 13, v[0:1]
	v_lshl_add_u64 v[0:1], v[34:35], 0, v[0:1]
	v_add_co_u32_e32 v0, vcc, s6, v0
	v_lshrrev_b32_e32 v34, 4, v207
	s_nop 0
	v_addc_co_u32_e32 v1, vcc, 0, v1, vcc
	global_load_dwordx4 v[4:7], v[0:1], off offset:1024
	s_nop 0
	global_load_dwordx4 v[0:3], v[0:1], off offset:1536
	s_waitcnt vmcnt(7)
	v_lshlrev_b32_e32 v46, 16, v20
	v_and_b32_e32 v47, 0xffff0000, v20
	v_cvt_f32_i32_e32 v20, v31
	v_mul_f32_e32 v35, 0xbfb8aa3b, v17
	v_bfe_u32 v17, v206, 2, 2
	v_lshl_or_b32 v76, v34, 3, v17
	v_sub_u32_e32 v17, 0x7f, v31
	v_cvt_f32_i32_e32 v17, v17
	v_lshlrev_b32_e32 v42, 16, v18
	v_and_b32_e32 v43, 0xffff0000, v18
	v_mul_f32_e32 v32, 0xbfb8aa3b, v32
	v_mul_f32_e32 v16, v35, v17
	v_exp_f32_e32 v103, v16
	v_lshlrev_b32_e32 v44, 16, v19
	v_and_b32_e32 v45, 0xffff0000, v19
	v_mul_f32_e32 v20, v32, v20
	v_mul_f32_e32 v16, v103, v42
	v_mul_f32_e32 v17, v103, v43
	v_cvt_pk_bf16_f32 v16, v16, v17
	v_mul_f32_e32 v17, v103, v44
	v_mul_f32_e32 v18, v103, v45
	v_cvt_pk_bf16_f32 v17, v17, v18
	v_mul_f32_e32 v18, v103, v46
	v_mul_f32_e32 v19, v103, v47
	v_lshlrev_b32_e32 v48, 16, v21
	v_and_b32_e32 v49, 0xffff0000, v21
	v_exp_f32_e32 v104, v20
	v_cvt_pk_bf16_f32 v18, v18, v19
	v_mul_f32_e32 v19, v103, v48
	v_mul_f32_e32 v21, v103, v49
	s_movk_i32 s9, 0x50
	v_cvt_pk_bf16_f32 v19, v19, v21
	v_mad_u64_u32 v[20:21], s[6:7], v31, s9, v[30:31]
	v_lshl_add_u32 v105, v20, 1, 0
	s_barrier
	ds_write_b128 v105, v[16:19]
	v_mul_f32_e32 v16, v104, v42
	v_mul_f32_e32 v17, v104, v43
	v_cvt_pk_bf16_f32 v16, v16, v17
	v_mul_f32_e32 v17, v104, v44
	v_mul_f32_e32 v18, v104, v45
	v_cvt_pk_bf16_f32 v17, v17, v18
	v_mul_f32_e32 v18, v104, v46
	v_mul_f32_e32 v19, v104, v47
	v_cvt_pk_bf16_f32 v18, v18, v19
	v_sub_u32_e32 v19, 0x7f, v37
	v_cvt_f32_i32_e32 v20, v19
	v_mul_f32_e32 v19, v104, v48
	v_mul_f32_e32 v21, v104, v49
	v_cvt_pk_bf16_f32 v19, v19, v21
	v_mul_f32_e32 v20, v35, v20
	v_exp_f32_e32 v35, v20
	v_cvt_f32_i32_e32 v20, v37
	ds_write_b128 v105, v[16:19] offset:20480
	s_waitcnt vmcnt(6)
	ds_write_b128 v105, v[22:25] offset:40960
	v_mad_u32_u24 v62, v76, s9, v62
	v_mad_u32_u24 v87, v76, s9, v80
	v_mul_f32_e32 v20, v32, v20
	v_exp_f32_e32 v32, v20
	s_waitcnt vmcnt(5)
	v_lshlrev_b32_e32 v22, 16, v26
	v_and_b32_e32 v23, 0xffff0000, v26
	v_mul_f32_e32 v16, v35, v22
	v_mul_f32_e32 v17, v35, v23
	v_lshlrev_b32_e32 v24, 16, v27
	v_and_b32_e32 v25, 0xffff0000, v27
	v_cvt_pk_bf16_f32 v16, v16, v17
	v_mul_f32_e32 v17, v35, v24
	v_mul_f32_e32 v18, v35, v25
	v_lshlrev_b32_e32 v26, 16, v28
	v_and_b32_e32 v27, 0xffff0000, v28
	v_cvt_pk_bf16_f32 v17, v17, v18
	v_mul_f32_e32 v18, v35, v26
	v_mul_f32_e32 v19, v35, v27
	v_lshlrev_b32_e32 v28, 16, v29
	v_and_b32_e32 v29, 0xffff0000, v29
	v_cvt_pk_bf16_f32 v18, v18, v19
	v_mul_f32_e32 v19, v35, v28
	v_mul_f32_e32 v21, v35, v29
	v_cvt_pk_bf16_f32 v19, v19, v21
	v_mad_u64_u32 v[20:21], s[6:7], v37, s9, v[30:31]
	v_lshl_add_u32 v37, v20, 1, 0
	ds_write_b128 v37, v[16:19]
	v_mul_f32_e32 v16, v32, v22
	v_mul_f32_e32 v17, v32, v23
	v_cvt_pk_bf16_f32 v16, v16, v17
	v_mul_f32_e32 v17, v32, v24
	v_mul_f32_e32 v18, v32, v25
	v_cvt_pk_bf16_f32 v17, v17, v18
	v_mul_f32_e32 v18, v32, v26
	v_mul_f32_e32 v19, v32, v27
	v_cvt_pk_bf16_f32 v18, v18, v19
	v_mul_f32_e32 v19, v32, v28
	v_mul_f32_e32 v20, v32, v29
	v_cvt_pk_bf16_f32 v19, v19, v20
	v_readlane_b32 s6, v254, 42
	v_mov_b32_e32 v30, 0xa00
	ds_write_b128 v37, v[16:19] offset:20480
	s_waitcnt vmcnt(4)
	ds_write_b128 v37, v[38:41] offset:40960
	v_or_b32_e32 v77, s6, v86
	v_mul_u32_u24_e32 v16, 0x50, v76
	v_mad_u32_u24 v46, v76, s9, v30
	v_mad_u32_u24 v17, v76, s9, v77
	v_or_b32_e32 v16, v16, v86
	v_add_u32_e32 v30, v46, v77
	v_or_b32_e32 v46, v46, v86
	v_add_u32_e32 v63, v62, v77
	v_or_b32_e32 v62, v62, v86
	v_or_b32_e32 v86, v87, v86
	v_lshl_add_u32 v106, v17, 1, 0
	v_lshl_add_u32 v107, v16, 1, s72
	v_lshl_add_u32 v109, v46, 1, s72
	v_lshl_add_u32 v110, v63, 1, 0
	v_lshl_add_u32 v111, v62, 1, s72
	v_add_u32_e32 v76, v87, v77
	v_lshl_add_u32 v113, v86, 1, s72
	s_waitcnt lgkmcnt(0)
	s_barrier
	ds_read_b64_tr_b16 v[16:17], v106 offset:40960
	ds_read_b64_tr_b16 v[18:19], v106 offset:41600
	ds_read_b64_tr_b16 v[20:21], v107
	ds_read_b64_tr_b16 v[24:25], v107 offset:32
	ds_read_b64_tr_b16 v[22:23], v107 offset:640
	ds_read_b64_tr_b16 v[26:27], v107 offset:672
	ds_read_b64_tr_b16 v[28:29], v107 offset:64
	ds_read_b64_tr_b16 v[38:39], v107 offset:96
	v_lshl_add_u32 v108, v30, 1, 0
	ds_read_b64_tr_b16 v[30:31], v107 offset:704
	ds_read_b64_tr_b16 v[40:41], v107 offset:736
	ds_read_b64_tr_b16 v[42:43], v108 offset:40960
	ds_read_b64_tr_b16 v[44:45], v108 offset:41600
	ds_read_b64_tr_b16 v[46:47], v109
	ds_read_b64_tr_b16 v[50:51], v109 offset:32
	ds_read_b64_tr_b16 v[54:55], v109 offset:64
	ds_read_b64_tr_b16 v[58:59], v109 offset:96
	ds_read_b64_tr_b16 v[48:49], v109 offset:640
	ds_read_b64_tr_b16 v[52:53], v109 offset:672
	ds_read_b64_tr_b16 v[56:57], v109 offset:704
	ds_read_b64_tr_b16 v[60:61], v109 offset:736
	ds_read_b64_tr_b16 v[62:63], v110 offset:40960
	ds_read_b64_tr_b16 v[64:65], v110 offset:41600
	ds_read_b64_tr_b16 v[66:67], v111
	ds_read_b64_tr_b16 v[70:71], v111 offset:32
	ds_read_b64_tr_b16 v[68:69], v111 offset:640
	ds_read_b64_tr_b16 v[72:73], v111 offset:672
	ds_read_b64_tr_b16 v[74:75], v111 offset:64
	ds_read_b64_tr_b16 v[78:79], v111 offset:96
	v_lshl_add_u32 v112, v76, 1, 0
	ds_read_b64_tr_b16 v[76:77], v111 offset:704
	ds_read_b64_tr_b16 v[80:81], v111 offset:736
	ds_read_b64_tr_b16 v[82:83], v112 offset:40960
	ds_read_b64_tr_b16 v[84:85], v112 offset:41600
	ds_read_b64_tr_b16 v[86:87], v113
	ds_read_b64_tr_b16 v[90:91], v113 offset:32
	ds_read_b64_tr_b16 v[94:95], v113 offset:64
	ds_read_b64_tr_b16 v[98:99], v113 offset:96
	ds_read_b64_tr_b16 v[88:89], v113 offset:640
	ds_read_b64_tr_b16 v[92:93], v113 offset:672
	ds_read_b64_tr_b16 v[96:97], v113 offset:704
	ds_read_b64_tr_b16 v[100:101], v113 offset:736
	v_lshlrev_b32_e32 v34, 10, v34
	s_waitcnt lgkmcnt(14)
	v_mfma_f32_16x16x32_bf16 v[20:23], v[16:19], v[20:23], 0
	v_readlane_b32 s6, v254, 40
	s_lshl_b32 s0, s0, 13
	v_readlane_b32 s7, v254, 55
	v_mfma_f32_16x16x32_bf16 v[24:27], v[16:19], v[24:27], 0
	v_add3_u32 v34, s6, v34, v102
	v_add_u32_e32 v34, 0xf000, v34
	s_add_i32 s0, s0, s7
	v_mfma_f32_16x16x32_bf16 v[28:31], v[16:19], v[28:31], 0
	v_readlane_b32 s20, v254, 19
	v_readlane_b32 s21, v254, 20
	v_readlane_b32 s22, v254, 21
	v_mfma_f32_16x16x32_bf16 v[16:19], v[16:19], v[38:41], 0
	v_readlane_b32 s23, v254, 22
	v_mfma_f32_16x16x32_bf16 v[20:23], v[42:45], v[46:49], v[20:23]
	v_mfma_f32_16x16x32_bf16 v[24:27], v[42:45], v[50:53], v[24:27]
	v_mfma_f32_16x16x32_bf16 v[28:31], v[42:45], v[54:57], v[28:31]
	v_mfma_f32_16x16x32_bf16 v[16:19], v[42:45], v[58:61], v[16:19]
	v_mfma_f32_16x16x32_bf16 v[20:23], v[62:65], v[66:69], v[20:23]
	v_mfma_f32_16x16x32_bf16 v[24:27], v[62:65], v[70:73], v[24:27]
	s_waitcnt lgkmcnt(11)
	v_mfma_f32_16x16x32_bf16 v[28:31], v[62:65], v[74:77], v[28:31]
	s_waitcnt lgkmcnt(10)
	v_mfma_f32_16x16x32_bf16 v[16:19], v[62:65], v[78:81], v[16:19]
	s_waitcnt lgkmcnt(3)
	v_mfma_f32_16x16x32_bf16 v[20:23], v[82:85], v[86:89], v[20:23]
	v_lshl_add_u32 v87, v207, 4, s6
	v_lshlrev_b32_e32 v86, 2, v207
	v_or_b32_e32 v38, s0, v86
	s_waitcnt lgkmcnt(2)
	v_mfma_f32_16x16x32_bf16 v[24:27], v[82:85], v[90:93], v[24:27]
	v_lshlrev_b32_e32 v38, 2, v38
	s_waitcnt lgkmcnt(1)
	v_mfma_f32_16x16x32_bf16 v[28:31], v[82:85], v[94:97], v[28:31]
	s_waitcnt lgkmcnt(0)
	v_mfma_f32_16x16x32_bf16 v[16:19], v[82:85], v[98:101], v[16:19]
	s_nop 2
	ds_write2_b32 v34, v20, v24 offset1:16
	ds_write2_b32 v34, v21, v25 offset0:64 offset1:80
	ds_write2_b32 v34, v22, v26 offset0:128 offset1:144
	ds_write2_b32 v34, v23, v27 offset0:192 offset1:208
	s_nop 0
	ds_write2_b32 v34, v28, v16 offset0:32 offset1:48
	ds_write2_b32 v34, v29, v17 offset0:96 offset1:112
	ds_write2_b32 v34, v30, v18 offset0:160 offset1:176
	ds_write2_b32 v34, v31, v19 offset0:224 offset1:240
	s_waitcnt lgkmcnt(0)
	ds_read_b128 v[16:19], v87 offset:61440
	ds_read_b128 v[20:23], v87 offset:62464
	ds_read_b128 v[24:27], v87 offset:63488
	ds_read_b128 v[28:31], v87 offset:64512
	s_waitcnt lgkmcnt(3)
	buffer_store_dwordx4 v[16:19], v38, s[20:23], 0 offen sc1
	s_waitcnt lgkmcnt(2)
	buffer_store_dwordx4 v[20:23], v38, s[20:23], 0 offen offset:1024 sc1
	s_waitcnt lgkmcnt(1)
	buffer_store_dwordx4 v[24:27], v38, s[20:23], 0 offen offset:2048 sc1
	s_waitcnt lgkmcnt(0)
	buffer_store_dwordx4 v[28:31], v38, s[20:23], 0 offen offset:3072 sc1
	s_waitcnt vmcnt(7)
	v_lshlrev_b32_e32 v16, 16, v12
	v_and_b32_e32 v18, 0xffff0000, v12
	v_mul_f32_e32 v17, v103, v16
	v_mul_f32_e32 v12, v103, v18
	v_cvt_pk_bf16_f32 v12, v17, v12
	v_lshlrev_b32_e32 v17, 16, v13
	v_and_b32_e32 v20, 0xffff0000, v13
	v_mul_f32_e32 v19, v103, v17
	v_mul_f32_e32 v13, v103, v20
	v_cvt_pk_bf16_f32 v13, v19, v13
	v_lshlrev_b32_e32 v19, 16, v14
	v_and_b32_e32 v22, 0xffff0000, v14
	v_mul_f32_e32 v21, v103, v19
	v_mul_f32_e32 v14, v103, v22
	v_cvt_pk_bf16_f32 v14, v21, v14
	v_lshlrev_b32_e32 v21, 16, v15
	v_and_b32_e32 v24, 0xffff0000, v15
	v_mul_f32_e32 v23, v103, v21
	v_mul_f32_e32 v15, v103, v24
	v_cvt_pk_bf16_f32 v15, v23, v15
	s_waitcnt lgkmcnt(0)
	s_barrier
	ds_write_b128 v105, v[12:15]
	v_mul_f32_e32 v12, v104, v16
	v_mul_f32_e32 v13, v104, v18
	v_cvt_pk_bf16_f32 v12, v12, v13
	v_mul_f32_e32 v13, v104, v17
	v_mul_f32_e32 v14, v104, v20
	v_cvt_pk_bf16_f32 v13, v13, v14
	v_mul_f32_e32 v14, v104, v19
	v_mul_f32_e32 v15, v104, v22
	v_cvt_pk_bf16_f32 v14, v14, v15
	v_mul_f32_e32 v15, v104, v21
	v_mul_f32_e32 v16, v104, v24
	v_cvt_pk_bf16_f32 v15, v15, v16
	ds_write_b128 v105, v[12:15] offset:20480
	s_waitcnt vmcnt(6)
	ds_write_b128 v105, v[8:11] offset:40960
	s_waitcnt vmcnt(5)
	v_lshlrev_b32_e32 v8, 16, v4
	v_and_b32_e32 v10, 0xffff0000, v4
	v_mul_f32_e32 v9, v35, v8
	v_mul_f32_e32 v4, v35, v10
	v_cvt_pk_bf16_f32 v4, v9, v4
	v_lshlrev_b32_e32 v9, 16, v5
	v_and_b32_e32 v12, 0xffff0000, v5
	v_mul_f32_e32 v11, v35, v9
	v_mul_f32_e32 v5, v35, v12
	v_cvt_pk_bf16_f32 v5, v11, v5
	v_lshlrev_b32_e32 v11, 16, v6
	v_and_b32_e32 v14, 0xffff0000, v6
	v_mul_f32_e32 v13, v35, v11
	v_mul_f32_e32 v6, v35, v14
	v_cvt_pk_bf16_f32 v6, v13, v6
	v_lshlrev_b32_e32 v13, 16, v7
	v_and_b32_e32 v16, 0xffff0000, v7
	v_mul_f32_e32 v15, v35, v13
	v_mul_f32_e32 v7, v35, v16
	v_cvt_pk_bf16_f32 v7, v15, v7
	ds_write_b128 v37, v[4:7]
	v_mul_f32_e32 v4, v32, v8
	v_mul_f32_e32 v5, v32, v10
	v_cvt_pk_bf16_f32 v4, v4, v5
	v_mul_f32_e32 v5, v32, v9
	v_mul_f32_e32 v6, v32, v12
	v_cvt_pk_bf16_f32 v5, v5, v6
	v_mul_f32_e32 v6, v32, v11
	v_mul_f32_e32 v7, v32, v14
	v_cvt_pk_bf16_f32 v6, v6, v7
	v_mul_f32_e32 v7, v32, v13
	v_mul_f32_e32 v8, v32, v16
	v_cvt_pk_bf16_f32 v7, v7, v8
	ds_write_b128 v37, v[4:7] offset:20480
	s_waitcnt vmcnt(4)
	ds_write_b128 v37, v[0:3] offset:40960
	s_waitcnt lgkmcnt(0)
	s_barrier
	ds_read_b64_tr_b16 v[0:1], v106 offset:40960
	ds_read_b64_tr_b16 v[2:3], v106 offset:41600
	ds_read_b64_tr_b16 v[4:5], v107
	ds_read_b64_tr_b16 v[8:9], v107 offset:32
	ds_read_b64_tr_b16 v[6:7], v107 offset:640
	ds_read_b64_tr_b16 v[10:11], v107 offset:672
	ds_read_b64_tr_b16 v[12:13], v107 offset:64
	ds_read_b64_tr_b16 v[16:17], v107 offset:96
	ds_read_b64_tr_b16 v[14:15], v107 offset:704
	ds_read_b64_tr_b16 v[18:19], v107 offset:736
	ds_read_b64_tr_b16 v[20:21], v108 offset:40960
	ds_read_b64_tr_b16 v[22:23], v108 offset:41600
	ds_read_b64_tr_b16 v[24:25], v109
	ds_read_b64_tr_b16 v[28:29], v109 offset:32
	ds_read_b64_tr_b16 v[38:39], v109 offset:64
	ds_read_b64_tr_b16 v[42:43], v109 offset:96
	ds_read_b64_tr_b16 v[26:27], v109 offset:640
	ds_read_b64_tr_b16 v[30:31], v109 offset:672
	ds_read_b64_tr_b16 v[40:41], v109 offset:704
	ds_read_b64_tr_b16 v[44:45], v109 offset:736
	ds_read_b64_tr_b16 v[46:47], v110 offset:40960
	ds_read_b64_tr_b16 v[48:49], v110 offset:41600
	ds_read_b64_tr_b16 v[50:51], v111
	ds_read_b64_tr_b16 v[54:55], v111 offset:32
	ds_read_b64_tr_b16 v[52:53], v111 offset:640
	ds_read_b64_tr_b16 v[56:57], v111 offset:672
	ds_read_b64_tr_b16 v[58:59], v111 offset:64
	ds_read_b64_tr_b16 v[62:63], v111 offset:96
	ds_read_b64_tr_b16 v[60:61], v111 offset:704
	ds_read_b64_tr_b16 v[64:65], v111 offset:736
	ds_read_b64_tr_b16 v[66:67], v112 offset:40960
	ds_read_b64_tr_b16 v[68:69], v112 offset:41600
	ds_read_b64_tr_b16 v[70:71], v113
	ds_read_b64_tr_b16 v[74:75], v113 offset:32
	ds_read_b64_tr_b16 v[78:79], v113 offset:64
	ds_read_b64_tr_b16 v[82:83], v113 offset:96
	ds_read_b64_tr_b16 v[72:73], v113 offset:640
	ds_read_b64_tr_b16 v[76:77], v113 offset:672
	ds_read_b64_tr_b16 v[80:81], v113 offset:704
	ds_read_b64_tr_b16 v[84:85], v113 offset:736
	s_waitcnt lgkmcnt(14)
	v_mfma_f32_16x16x32_bf16 v[4:7], v[0:3], v[4:7], 0
	s_lshl_b32 s0, s8, 13
	s_add_i32 s0, s0, s7
	s_lshl_b32 s6, s5, 8
	v_mfma_f32_16x16x32_bf16 v[8:11], v[0:3], v[8:11], 0
	s_ashr_i32 s7, s6, 31
	s_lshl_b64 s[6:7], s[6:7], 2
	v_mfma_f32_16x16x32_bf16 v[12:15], v[0:3], v[12:15], 0
	v_mfma_f32_16x16x32_bf16 v[0:3], v[0:3], v[16:19], 0
	v_or_b32_e32 v16, s0, v86
	v_lshlrev_b32_e32 v16, 2, v16
	s_add_u32 s0, s48, s6
	v_mfma_f32_16x16x32_bf16 v[4:7], v[20:23], v[24:27], v[4:7]
	s_addc_u32 s6, s49, s7
	s_add_u32 s76, s0, 0x53c0
	s_addc_u32 s77, s6, 0
	v_mfma_f32_16x16x32_bf16 v[8:11], v[20:23], v[28:31], v[8:11]
	v_mfma_f32_16x16x32_bf16 v[12:15], v[20:23], v[38:41], v[12:15]
	v_mfma_f32_16x16x32_bf16 v[0:3], v[20:23], v[42:45], v[0:3]
	v_mfma_f32_16x16x32_bf16 v[4:7], v[46:49], v[50:53], v[4:7]
	v_mfma_f32_16x16x32_bf16 v[8:11], v[46:49], v[54:57], v[8:11]
	s_waitcnt lgkmcnt(11)
	v_mfma_f32_16x16x32_bf16 v[12:15], v[46:49], v[58:61], v[12:15]
	s_waitcnt lgkmcnt(10)
	v_mfma_f32_16x16x32_bf16 v[0:3], v[46:49], v[62:65], v[0:3]
	s_waitcnt lgkmcnt(3)
	v_mfma_f32_16x16x32_bf16 v[4:7], v[66:69], v[70:73], v[4:7]
	s_waitcnt lgkmcnt(2)
	v_mfma_f32_16x16x32_bf16 v[8:11], v[66:69], v[74:77], v[8:11]
	s_waitcnt lgkmcnt(1)
	v_mfma_f32_16x16x32_bf16 v[12:15], v[66:69], v[78:81], v[12:15]
	s_waitcnt lgkmcnt(0)
	v_mfma_f32_16x16x32_bf16 v[0:3], v[66:69], v[82:85], v[0:3]
	s_nop 3
	ds_write2_b32 v34, v4, v8 offset1:16
	ds_write2_b32 v34, v5, v9 offset0:64 offset1:80
	ds_write2_b32 v34, v6, v10 offset0:128 offset1:144
	ds_write2_b32 v34, v7, v11 offset0:192 offset1:208
	ds_write2_b32 v34, v12, v0 offset0:32 offset1:48
	ds_write2_b32 v34, v13, v1 offset0:96 offset1:112
	ds_write2_b32 v34, v14, v2 offset0:160 offset1:176
	ds_write2_b32 v34, v15, v3 offset0:224 offset1:240
	s_waitcnt lgkmcnt(0)
	ds_read_b128 v[0:3], v87 offset:61440
	ds_read_b128 v[4:7], v87 offset:62464
	ds_read_b128 v[8:11], v87 offset:63488
	ds_read_b128 v[12:15], v87 offset:64512
	s_waitcnt lgkmcnt(3)
	buffer_store_dwordx4 v[0:3], v16, s[20:23], 0 offen sc1
	s_waitcnt lgkmcnt(2)
	buffer_store_dwordx4 v[4:7], v16, s[20:23], 0 offen offset:1024 sc1
	s_waitcnt lgkmcnt(1)
	buffer_store_dwordx4 v[8:11], v16, s[20:23], 0 offen offset:2048 sc1
	s_waitcnt lgkmcnt(0)
	buffer_store_dwordx4 v[12:15], v16, s[20:23], 0 offen offset:3072 sc1
	s_waitcnt lgkmcnt(0)

.LBB0_653:
	s_mul_hi_u32 s0, s12, 0xaaaaaaab
	s_lshr_b32 s13, s0, 1
	s_mul_i32 s16, s13, -3
	s_add_i32 s16, s16, s12
	s_cmp_lt_i32 s16, 2
	s_mov_b64 s[6:7], -1
	s_cbranch_scc1 .LBB0_656
	s_mov_b64 s[6:7], 0
	s_mov_b64 s[10:11], -1
	s_cmp_eq_u32 s16, 2
	s_mov_b32 s95, s13
	s_mov_b64 s[76:77], 0
	s_mov_b32 s94, s18
	s_cbranch_scc0 .LBB0_656
	s_lshl_b32 s8, s13, 1
	s_mul_hi_u32 s0, s8, 0x78787879
	s_lshr_b32 s0, s0, 4
	s_mul_i32 s0, s0, 34
	s_sub_i32 s0, s8, s0
	s_mul_hi_u32 s9, s12, 0xa0a0a0a1
	s_lshr_b32 s10, s9, 5
	s_lshr_b32 s19, s9, 7
	s_bfe_u32 s11, s9, 0x20005
	s_lshl_b32 s9, s0, 7
	s_cmp_eq_u32 s0, 0
	s_movk_i32 s21, 0xff00
	s_cselect_b32 s17, 8, 12
	s_cselect_b32 s20, 0x4000, s21
	s_or_b32 s8, s8, 1
	s_add_i32 s20, s20, s9
	s_mul_hi_u32 s9, s8, 0x78787879
	s_lshr_b32 s9, s9, 4
	s_lshl_b32 s17, s19, s17
	s_mul_i32 s9, s9, 34
	s_add_i32 s20, s20, s17
	s_sub_i32 s17, s8, s9
	s_lshl_b32 s8, s17, 7
	s_cmp_eq_u32 s17, 1
	s_cselect_b32 s9, 8, 12
	s_cselect_b32 s21, 0x4000, s21
	s_lshl_b32 s9, s19, s9
	s_add_i32 s19, s21, s8
	s_lshl_b32 s8, s5, 3
	s_or_b32 s8, s8, s11
	s_add_i32 s19, s19, s9
	s_ashr_i32 s9, s8, 31
	s_lshl_b64 s[8:9], s[8:9], 2
	s_add_u32 s8, s42, s8
	s_addc_u32 s9, s43, s9
	s_load_dword s100, s[8:9], 0x0
	s_load_dword s101, s[8:9], 0x10
	s_mov_b32 s8, 0xbfb8aa3b
	s_mov_b32 s9, 0x3f317218
	s_mov_b32 s21, 0x7f800000
	s_mov_b32 s22, 0x33800000
	v_ashrrev_i32_e32 v31, 3, v206
	v_and_b32_e32 v16, 15, v206
	v_lshlrev_b32_e32 v102, 2, v16
	v_and_b32_e32 v86, 12, v102
	v_mov_b32_e32 v62, 0x1400
	v_mov_b32_e32 v80, 0x1e00
	s_mov_b32 s94, 2
	s_waitcnt lgkmcnt(0)
	v_mov_b32_e32 v0, s100
	v_mov_b32_e32 v1, s101
	v_mul_f32_e32 v2, 0xbfb8aa3b, v0
	v_mul_f32_e32 v3, 0xbfb8aa3b, v1
	v_fma_f32 v4, v0, s8, -v2
	v_rndne_f32_e32 v5, v2
	v_fma_f32 v6, v1, s8, -v3
	v_rndne_f32_e32 v7, v3
	v_fmac_f32_e32 v4, 0xb2a5705f, v0
	v_sub_f32_e32 v2, v2, v5
	v_fmac_f32_e32 v6, 0xb2a5705f, v1
	v_sub_f32_e32 v3, v3, v7
	v_add_f32_e32 v2, v2, v4
	v_cvt_i32_f32_e32 v5, v5
	v_add_f32_e32 v3, v3, v6
	v_exp_f32_e32 v2, v2
	v_cvt_i32_f32_e32 v7, v7
	v_exp_f32_e32 v3, v3
	s_mov_b32 s8, 0x42ce8ed0
	v_ldexp_f32 v2, v2, v5
	v_cmp_nlt_f32_e32 vcc, s8, v0
	v_ldexp_f32 v3, v3, v7
	s_nop 0
	v_cndmask_b32_e32 v2, 0, v2, vcc
	v_cmp_nlt_f32_e32 vcc, s8, v1
	s_mov_b32 s8, 0xc2b17218
	s_nop 0
	v_cndmask_b32_e32 v3, 0, v3, vcc
	v_cmp_ngt_f32_e32 vcc, s8, v0
	s_nop 1
	v_cndmask_b32_e32 v17, v227, v2, vcc
	v_cmp_ngt_f32_e32 vcc, s8, v1
	v_add_f32_e32 v1, 1.0, v17
	v_add_f32_e32 v4, -1.0, v1
	v_cndmask_b32_e32 v0, v227, v3, vcc
	v_add_f32_e32 v20, 1.0, v0
	v_frexp_mant_f32_e32 v5, v1
	v_cvt_f64_f32_e32 v[2:3], v1
	s_mov_b32 s8, 0x3f2aaaab
	v_add_f32_e32 v21, -1.0, v20
	v_sub_f32_e32 v6, v4, v1
	v_frexp_exp_i32_f64_e32 v2, v[2:3]
	v_cmp_gt_f32_e32 vcc, s8, v5
	v_sub_f32_e32 v4, v17, v4
	v_sub_f32_e32 v3, v21, v20
	v_add_f32_e32 v6, 1.0, v6
	v_subbrev_co_u32_e32 v2, vcc, 0, v2, vcc
	v_add_f32_e32 v22, 1.0, v3
	v_add_f32_e32 v3, v4, v6
	v_sub_u32_e32 v4, 0, v2
	v_ldexp_f32 v1, v1, v4
	v_ldexp_f32 v3, v3, v4
	v_add_f32_e32 v4, -1.0, v1
	v_add_f32_e32 v6, 1.0, v1
	v_add_f32_e32 v5, 1.0, v4
	v_add_f32_e32 v7, -1.0, v6
	v_sub_f32_e32 v5, v1, v5
	v_sub_f32_e32 v1, v1, v7
	v_add_f32_e32 v1, v3, v1
	v_add_f32_e32 v7, v3, v5
	v_add_f32_e32 v3, v6, v1
	v_rcp_f32_e32 v10, v3
	v_add_f32_e32 v5, v4, v7
	v_sub_f32_e32 v6, v6, v3
	v_add_f32_e32 v1, v1, v6
	v_mul_f32_e32 v12, v5, v10
	v_mul_f32_e32 v6, v3, v12
	v_fma_f32 v8, v12, v3, -v6
	v_sub_f32_e32 v4, v4, v5
	v_fmac_f32_e32 v8, v12, v1
	v_add_f32_e32 v11, v7, v4
	v_add_f32_e32 v4, v6, v8
	v_sub_f32_e32 v7, v5, v4
	v_mov_b32_e32 v9, v4
	v_pk_add_f32 v[4:5], v[4:5], v[6:7] neg_lo:[0,1] neg_hi:[0,1]
	v_cvt_f32_i32_e32 v2, v2
	v_pk_add_f32 v[4:5], v[4:5], v[8:9] neg_lo:[0,1] neg_hi:[0,1]
	v_cmp_neq_f32_e32 vcc, s21, v17
	v_add_f32_e32 v5, v11, v5
	v_add_f32_e32 v4, v4, v5
	v_add_f32_e32 v5, v7, v4
	v_mul_f32_e32 v9, v10, v5
	v_mul_f32_e32 v6, v3, v9
	v_fma_f32 v8, v9, v3, -v6
	v_sub_f32_e32 v7, v7, v5
	v_fmac_f32_e32 v8, v9, v1
	v_add_f32_e32 v11, v4, v7
	v_add_f32_e32 v13, v12, v9
	v_add_f32_e32 v4, v6, v8
	v_sub_f32_e32 v3, v13, v12
	v_sub_f32_e32 v7, v5, v4
	v_sub_f32_e32 v1, v9, v3
	v_mov_b32_e32 v9, v4
	v_pk_add_f32 v[4:5], v[4:5], v[6:7] neg_lo:[0,1] neg_hi:[0,1]
	s_nop 0
	v_pk_add_f32 v[4:5], v[4:5], v[8:9] neg_lo:[0,1] neg_hi:[0,1]
	s_nop 0
	v_add_f32_e32 v3, v11, v5
	v_add_f32_e32 v3, v4, v3
	v_add_f32_e32 v3, v7, v3
	v_mul_f32_e32 v3, v10, v3
	v_add_f32_e32 v1, v1, v3
	v_add_f32_e32 v3, v13, v1
	v_mul_f32_e32 v4, v3, v3
	v_fmamk_f32 v7, v4, 0x3e9b6dac, v252
	v_sub_f32_e32 v6, v3, v13
	v_ldexp_f32 v5, v3, 1
	v_mul_f32_e32 v3, v3, v4
	v_fmaak_f32 v201, v4, v7, 0x3f2aaada
	v_sub_f32_e32 v1, v1, v6
	v_pk_mul_f32 v[6:7], v[2:3], v[200:201]
	v_ldexp_f32 v1, v1, 1
	v_fma_f32 v4, v2, s9, -v6
	v_fmac_f32_e32 v4, 0xb102e308, v2
	v_pk_add_f32 v[2:3], v[6:7], v[4:5]
	v_mov_b32_e32 v8, v6
	v_sub_f32_e32 v9, v3, v5
	v_pk_add_f32 v[10:11], v[2:3], v[6:7] neg_lo:[0,1] neg_hi:[0,1]
	v_sub_f32_e32 v7, v7, v9
	v_add_f32_e32 v9, v1, v7
	v_pk_add_f32 v[14:15], v[2:3], v[8:9]
	v_mov_b32_e32 v5, v2
	v_mov_b32_e32 v11, v15
	v_pk_add_f32 v[18:19], v[4:5], v[10:11] neg_lo:[0,1] neg_hi:[0,1]
	v_pk_add_f32 v[4:5], v[4:5], v[10:11]
	v_mov_b32_e32 v6, v3
	v_mov_b32_e32 v13, v2
	v_pk_add_f32 v[2:3], v[4:5], v[2:3] op_sel:[1,0] op_sel_hi:[0,1] neg_lo:[0,1] neg_hi:[0,1]
	v_mov_b32_e32 v12, v9
	v_mov_b32_e32 v8, v15
	v_mov_b32_e32 v9, v5
	v_mov_b32_e32 v7, v2
	v_pk_add_f32 v[10:11], v[14:15], v[2:3] op_sel_hi:[1,0] neg_lo:[0,1] neg_hi:[0,1]
	v_pk_add_f32 v[2:3], v[8:9], v[6:7] neg_lo:[0,1] neg_hi:[0,1]
	v_mov_b32_e32 v10, v18
	v_pk_add_f32 v[2:3], v[12:13], v[2:3] neg_lo:[0,1] neg_hi:[0,1]
	v_mov_b32_e32 v19, v5
	v_pk_add_f32 v[6:7], v[10:11], v[2:3]
	s_nop 0
	v_pk_add_f32 v[8:9], v[6:7], v[6:7] op_sel:[0,1] op_sel_hi:[1,0]
	s_nop 0
	v_pk_add_f32 v[4:5], v[4:5], v[8:9] op_sel:[1,0] op_sel_hi:[0,1]
	v_mov_b32_e32 v7, v4
	v_mov_b32_e32 v3, v8
	v_pk_add_f32 v[8:9], v[6:7], v[18:19] neg_lo:[0,1] neg_hi:[0,1]
	s_nop 0
	v_sub_f32_e32 v1, v6, v8
	v_pk_add_f32 v[2:3], v[2:3], v[8:9] neg_lo:[0,1] neg_hi:[0,1]
	v_sub_f32_e32 v1, v18, v1
	v_add_f32_e32 v1, v2, v1
	v_add_f32_e32 v1, v1, v3
	v_add_f32_e32 v1, v4, v1
	v_cndmask_b32_e32 v1, v227, v1, vcc
	v_cmp_lt_f32_e64 vcc, |v17|, s22
	v_frexp_mant_f32_e32 v4, v20
	v_cvt_f64_f32_e32 v[2:3], v20
	v_cndmask_b32_e32 v17, v1, v17, vcc
	v_frexp_exp_i32_f64_e32 v2, v[2:3]
	v_cmp_gt_f32_e32 vcc, s8, v4
	v_sub_f32_e32 v1, v0, v21
	v_add_f32_e32 v1, v1, v22
	v_subbrev_co_u32_e32 v10, vcc, 0, v2, vcc
	v_sub_u32_e32 v2, 0, v10
	v_ldexp_f32 v3, v20, v2
	v_ldexp_f32 v1, v1, v2
	v_add_f32_e32 v2, -1.0, v3
	v_add_f32_e32 v5, 1.0, v3
	v_add_f32_e32 v4, 1.0, v2
	v_add_f32_e32 v6, -1.0, v5
	v_sub_f32_e32 v4, v3, v4
	v_sub_f32_e32 v3, v3, v6
	v_add_f32_e32 v4, v1, v4
	v_add_f32_e32 v1, v1, v3
	v_add_f32_e32 v11, v5, v1
	v_rcp_f32_e32 v12, v11
	v_sub_f32_e32 v3, v5, v11
	v_add_f32_e32 v1, v1, v3
	v_add_f32_e32 v3, v2, v4
	v_sub_f32_e32 v2, v2, v3
	v_mul_f32_e32 v14, v3, v12
	v_add_f32_e32 v13, v4, v2
	v_mul_f32_e32 v4, v11, v14
	v_fma_f32 v6, v14, v11, -v4
	v_fmac_f32_e32 v6, v14, v1
	v_add_f32_e32 v2, v4, v6
	v_sub_f32_e32 v5, v3, v2
	v_pk_add_f32 v[8:9], v[2:3], v[4:5] neg_lo:[0,1] neg_hi:[0,1]
	v_mov_b32_e32 v7, v2
	v_pk_add_f32 v[2:3], v[8:9], v[6:7] neg_lo:[0,1] neg_hi:[0,1]
	s_lshl_b32 s8, s11, 7
	v_add_f32_e32 v3, v13, v3
	v_add_f32_e32 v2, v2, v3
	v_add_f32_e32 v3, v5, v2
	v_mul_f32_e32 v13, v12, v3
	v_mul_f32_e32 v4, v11, v13
	v_fma_f32 v6, v13, v11, -v4
	v_fmac_f32_e32 v6, v13, v1
	v_sub_f32_e32 v1, v5, v3
	v_add_f32_e32 v1, v2, v1
	v_add_f32_e32 v2, v4, v6
	v_sub_f32_e32 v5, v3, v2
	v_pk_add_f32 v[8:9], v[2:3], v[4:5] neg_lo:[0,1] neg_hi:[0,1]
	v_mov_b32_e32 v7, v2
	v_pk_add_f32 v[2:3], v[8:9], v[6:7] neg_lo:[0,1] neg_hi:[0,1]
	s_add_u32 s8, s70, s8
	v_add_f32_e32 v1, v1, v3
	v_add_f32_e32 v1, v2, v1
	v_add_f32_e32 v3, v14, v13
	v_add_f32_e32 v1, v5, v1
	v_sub_f32_e32 v2, v3, v14
	v_mul_f32_e32 v1, v12, v1
	v_sub_f32_e32 v2, v13, v2
	v_add_f32_e32 v1, v2, v1
	v_add_f32_e32 v4, v3, v1
	v_mul_f32_e32 v6, v4, v4
	v_fmamk_f32 v2, v6, 0x3e9b6dac, v252
	v_fmaak_f32 v201, v6, v2, 0x3f2aaada
	v_cvt_f32_i32_e32 v2, v10
	v_sub_f32_e32 v3, v4, v3
	v_sub_f32_e32 v1, v1, v3
	v_mul_f32_e32 v3, v4, v6
	v_pk_mul_f32 v[6:7], v[2:3], v[200:201]
	v_ldexp_f32 v5, v4, 1
	v_fma_f32 v4, v2, s9, -v6
	v_fmac_f32_e32 v4, 0xb102e308, v2
	v_pk_add_f32 v[2:3], v[6:7], v[4:5]
	v_ldexp_f32 v1, v1, 1
	v_sub_f32_e32 v5, v3, v5
	v_sub_f32_e32 v5, v7, v5
	v_add_f32_e32 v9, v1, v5
	v_lshlrev_b32_e32 v1, 3, v206
	v_and_b32_e32 v30, 56, v1
	v_add_u32_e32 v12, s20, v31
	v_mov_b32_e32 v8, v6
	s_addc_u32 s9, s71, 0
	v_lshlrev_b32_e32 v32, 1, v30
	v_ashrrev_i32_e32 v13, 31, v12
	v_pk_add_f32 v[6:7], v[2:3], v[6:7] neg_lo:[0,1] neg_hi:[0,1]
	v_pk_add_f32 v[10:11], v[2:3], v[8:9]
	v_lshl_add_u64 v[34:35], s[8:9], 0, v[32:33]
	v_lshlrev_b64 v[12:13], 13, v[12:13]
	v_lshl_add_u64 v[12:13], v[34:35], 0, v[12:13]
	s_movk_i32 s8, 0x1000
	v_mov_b32_e32 v7, v11
	v_mov_b32_e32 v5, v2
	v_add_co_u32_e32 v12, vcc, s8, v12
	v_pk_add_f32 v[14:15], v[4:5], v[6:7] neg_lo:[0,1] neg_hi:[0,1]
	v_pk_add_f32 v[4:5], v[4:5], v[6:7]
	v_addc_co_u32_e32 v13, vcc, 0, v13, vcc
	v_pk_add_f32 v[6:7], v[4:5], v[2:3] op_sel:[1,0] op_sel_hi:[0,1] neg_lo:[0,1] neg_hi:[0,1]
	global_load_dwordx4 v[18:21], v[12:13], off offset:1024
	v_pk_add_f32 v[22:23], v[10:11], v[6:7] op_sel_hi:[1,0] neg_lo:[0,1] neg_hi:[0,1]
	v_mov_b32_e32 v10, v11
	v_mov_b32_e32 v11, v5
	v_mov_b32_e32 v24, v3
	v_mov_b32_e32 v25, v6
	v_pk_add_f32 v[6:7], v[10:11], v[24:25] neg_lo:[0,1] neg_hi:[0,1]
	v_mov_b32_e32 v8, v9
	v_mov_b32_e32 v9, v2
	v_pk_add_f32 v[2:3], v[8:9], v[6:7] neg_lo:[0,1] neg_hi:[0,1]
	v_mov_b32_e32 v22, v14
	v_pk_add_f32 v[6:7], v[22:23], v[2:3]
	v_mov_b32_e32 v15, v5
	v_pk_add_f32 v[8:9], v[6:7], v[6:7] op_sel:[0,1] op_sel_hi:[1,0]
	v_cmp_neq_f32_e32 vcc, s21, v0
	v_pk_add_f32 v[4:5], v[4:5], v[8:9] op_sel:[1,0] op_sel_hi:[0,1]
	v_mov_b32_e32 v7, v4
	v_pk_add_f32 v[10:11], v[6:7], v[14:15] neg_lo:[0,1] neg_hi:[0,1]
	v_mov_b32_e32 v3, v8
	v_sub_f32_e32 v1, v6, v10
	v_pk_add_f32 v[2:3], v[2:3], v[10:11] neg_lo:[0,1] neg_hi:[0,1]
	v_sub_f32_e32 v1, v14, v1
	v_add_f32_e32 v1, v2, v1
	v_add_f32_e32 v1, v1, v3
	v_add_f32_e32 v1, v4, v1
	v_cndmask_b32_e32 v1, v227, v1, vcc
	v_cmp_lt_f32_e64 vcc, |v0|, s22
	global_load_dwordx4 v[22:25], v[12:13], off offset:1536
	v_cndmask_b32_e32 v32, v1, v0, vcc
	v_add_u32_e32 v0, 0x200, v206
	v_ashrrev_i32_e32 v37, 3, v0
	v_add_u32_e32 v0, s20, v37
	v_ashrrev_i32_e32 v1, 31, v0
	v_lshlrev_b64 v[0:1], 13, v[0:1]
	v_lshl_add_u64 v[0:1], v[34:35], 0, v[0:1]
	v_add_co_u32_e32 v0, vcc, s8, v0
	s_nop 0
	v_addc_co_u32_e32 v1, vcc, 0, v1, vcc
	global_load_dwordx4 v[26:29], v[0:1], off offset:1024
	global_load_dwordx4 v[38:41], v[0:1], off offset:1536
	v_add_u32_e32 v0, s19, v31
	v_ashrrev_i32_e32 v1, 31, v0
	v_lshlrev_b64 v[0:1], 13, v[0:1]
	v_lshl_add_u64 v[0:1], v[34:35], 0, v[0:1]
	v_add_co_u32_e32 v0, vcc, s8, v0
	s_nop 0
	v_addc_co_u32_e32 v1, vcc, 0, v1, vcc
	global_load_dwordx4 v[12:15], v[0:1], off offset:1024
	global_load_dwordx4 v[8:11], v[0:1], off offset:1536
	v_add_u32_e32 v0, s19, v37
	v_ashrrev_i32_e32 v1, 31, v0
	v_lshlrev_b64 v[0:1], 13, v[0:1]
	v_lshl_add_u64 v[0:1], v[34:35], 0, v[0:1]
	v_add_co_u32_e32 v0, vcc, s8, v0
	v_lshrrev_b32_e32 v34, 4, v207
	s_nop 0
	v_addc_co_u32_e32 v1, vcc, 0, v1, vcc
	global_load_dwordx4 v[4:7], v[0:1], off offset:1024
	s_nop 0
	global_load_dwordx4 v[0:3], v[0:1], off offset:1536
	s_waitcnt vmcnt(7)
	v_lshlrev_b32_e32 v46, 16, v20
	v_and_b32_e32 v47, 0xffff0000, v20
	v_cvt_f32_i32_e32 v20, v31
	v_mul_f32_e32 v35, 0xbfb8aa3b, v17
	v_bfe_u32 v17, v206, 2, 2
	v_lshl_or_b32 v76, v34, 3, v17
	v_sub_u32_e32 v17, 0x7f, v31
	v_cvt_f32_i32_e32 v17, v17
	v_lshlrev_b32_e32 v42, 16, v18
	v_and_b32_e32 v43, 0xffff0000, v18
	v_mul_f32_e32 v32, 0xbfb8aa3b, v32
	v_mul_f32_e32 v16, v35, v17
	v_exp_f32_e32 v103, v16
	v_lshlrev_b32_e32 v44, 16, v19
	v_and_b32_e32 v45, 0xffff0000, v19
	v_mul_f32_e32 v20, v32, v20
	v_mul_f32_e32 v16, v103, v42
	v_mul_f32_e32 v17, v103, v43
	v_cvt_pk_bf16_f32 v16, v16, v17
	v_mul_f32_e32 v17, v103, v44
	v_mul_f32_e32 v18, v103, v45
	v_cvt_pk_bf16_f32 v17, v17, v18
	v_mul_f32_e32 v18, v103, v46
	v_mul_f32_e32 v19, v103, v47
	v_lshlrev_b32_e32 v48, 16, v21
	v_and_b32_e32 v49, 0xffff0000, v21
	v_exp_f32_e32 v104, v20
	v_cvt_pk_bf16_f32 v18, v18, v19
	v_mul_f32_e32 v19, v103, v48
	v_mul_f32_e32 v21, v103, v49
	s_movk_i32 s19, 0x50
	v_cvt_pk_bf16_f32 v19, v19, v21
	v_mad_u64_u32 v[20:21], s[8:9], v31, s19, v[30:31]
	v_lshl_add_u32 v105, v20, 1, 0
	s_barrier
	ds_write_b128 v105, v[16:19]
	v_mul_f32_e32 v16, v104, v42
	v_mul_f32_e32 v17, v104, v43
	v_cvt_pk_bf16_f32 v16, v16, v17
	v_mul_f32_e32 v17, v104, v44
	v_mul_f32_e32 v18, v104, v45
	v_cvt_pk_bf16_f32 v17, v17, v18
	v_mul_f32_e32 v18, v104, v46
	v_mul_f32_e32 v19, v104, v47
	v_cvt_pk_bf16_f32 v18, v18, v19
	v_sub_u32_e32 v19, 0x7f, v37
	v_cvt_f32_i32_e32 v20, v19
	v_mul_f32_e32 v19, v104, v48
	v_mul_f32_e32 v21, v104, v49
	v_cvt_pk_bf16_f32 v19, v19, v21
	v_mul_f32_e32 v20, v35, v20
	v_exp_f32_e32 v35, v20
	v_cvt_f32_i32_e32 v20, v37
	ds_write_b128 v105, v[16:19] offset:20480
	s_waitcnt vmcnt(6)
	ds_write_b128 v105, v[22:25] offset:40960
	v_mad_u32_u24 v62, v76, s19, v62
	v_mad_u32_u24 v87, v76, s19, v80
	v_mul_f32_e32 v20, v32, v20
	v_exp_f32_e32 v32, v20
	s_waitcnt vmcnt(5)
	v_lshlrev_b32_e32 v22, 16, v26
	v_and_b32_e32 v23, 0xffff0000, v26
	v_mul_f32_e32 v16, v35, v22
	v_mul_f32_e32 v17, v35, v23
	v_lshlrev_b32_e32 v24, 16, v27
	v_and_b32_e32 v25, 0xffff0000, v27
	v_cvt_pk_bf16_f32 v16, v16, v17
	v_mul_f32_e32 v17, v35, v24
	v_mul_f32_e32 v18, v35, v25
	v_lshlrev_b32_e32 v26, 16, v28
	v_and_b32_e32 v27, 0xffff0000, v28
	v_cvt_pk_bf16_f32 v17, v17, v18
	v_mul_f32_e32 v18, v35, v26
	v_mul_f32_e32 v19, v35, v27
	v_lshlrev_b32_e32 v28, 16, v29
	v_and_b32_e32 v29, 0xffff0000, v29
	v_cvt_pk_bf16_f32 v18, v18, v19
	v_mul_f32_e32 v19, v35, v28
	v_mul_f32_e32 v21, v35, v29
	v_cvt_pk_bf16_f32 v19, v19, v21
	v_mad_u64_u32 v[20:21], s[8:9], v37, s19, v[30:31]
	v_lshl_add_u32 v37, v20, 1, 0
	ds_write_b128 v37, v[16:19]
	v_mul_f32_e32 v16, v32, v22
	v_mul_f32_e32 v17, v32, v23
	v_cvt_pk_bf16_f32 v16, v16, v17
	v_mul_f32_e32 v17, v32, v24
	v_mul_f32_e32 v18, v32, v25
	v_cvt_pk_bf16_f32 v17, v17, v18
	v_mul_f32_e32 v18, v32, v26
	v_mul_f32_e32 v19, v32, v27
	v_cvt_pk_bf16_f32 v18, v18, v19
	v_mul_f32_e32 v19, v32, v28
	v_mul_f32_e32 v20, v32, v29
	v_cvt_pk_bf16_f32 v19, v19, v20
	v_readlane_b32 s8, v254, 42
	v_mov_b32_e32 v30, 0xa00
	ds_write_b128 v37, v[16:19] offset:20480
	s_waitcnt vmcnt(4)
	ds_write_b128 v37, v[38:41] offset:40960
	v_or_b32_e32 v77, s8, v86
	v_mul_u32_u24_e32 v16, 0x50, v76
	v_mad_u32_u24 v46, v76, s19, v30
	v_mad_u32_u24 v17, v76, s19, v77
	v_or_b32_e32 v16, v16, v86
	v_add_u32_e32 v30, v46, v77
	v_or_b32_e32 v46, v46, v86
	v_add_u32_e32 v63, v62, v77
	v_or_b32_e32 v62, v62, v86
	v_or_b32_e32 v86, v87, v86
	v_lshl_add_u32 v106, v17, 1, 0
	v_lshl_add_u32 v107, v16, 1, s72
	v_lshl_add_u32 v109, v46, 1, s72
	v_lshl_add_u32 v110, v63, 1, 0
	v_lshl_add_u32 v111, v62, 1, s72
	v_add_u32_e32 v76, v87, v77
	v_lshl_add_u32 v113, v86, 1, s72
	s_waitcnt lgkmcnt(0)
	s_barrier
	ds_read_b64_tr_b16 v[16:17], v106 offset:40960
	ds_read_b64_tr_b16 v[18:19], v106 offset:41600
	ds_read_b64_tr_b16 v[20:21], v107
	ds_read_b64_tr_b16 v[24:25], v107 offset:32
	ds_read_b64_tr_b16 v[22:23], v107 offset:640
	ds_read_b64_tr_b16 v[26:27], v107 offset:672
	ds_read_b64_tr_b16 v[28:29], v107 offset:64
	ds_read_b64_tr_b16 v[38:39], v107 offset:96
	v_lshl_add_u32 v108, v30, 1, 0
	ds_read_b64_tr_b16 v[30:31], v107 offset:704
	ds_read_b64_tr_b16 v[40:41], v107 offset:736
	ds_read_b64_tr_b16 v[42:43], v108 offset:40960
	ds_read_b64_tr_b16 v[44:45], v108 offset:41600
	ds_read_b64_tr_b16 v[46:47], v109
	ds_read_b64_tr_b16 v[50:51], v109 offset:32
	ds_read_b64_tr_b16 v[54:55], v109 offset:64
	ds_read_b64_tr_b16 v[58:59], v109 offset:96
	ds_read_b64_tr_b16 v[48:49], v109 offset:640
	ds_read_b64_tr_b16 v[52:53], v109 offset:672
	ds_read_b64_tr_b16 v[56:57], v109 offset:704
	ds_read_b64_tr_b16 v[60:61], v109 offset:736
	ds_read_b64_tr_b16 v[62:63], v110 offset:40960
	ds_read_b64_tr_b16 v[64:65], v110 offset:41600
	ds_read_b64_tr_b16 v[66:67], v111
	ds_read_b64_tr_b16 v[70:71], v111 offset:32
	ds_read_b64_tr_b16 v[68:69], v111 offset:640
	ds_read_b64_tr_b16 v[72:73], v111 offset:672
	ds_read_b64_tr_b16 v[74:75], v111 offset:64
	ds_read_b64_tr_b16 v[78:79], v111 offset:96
	v_lshl_add_u32 v112, v76, 1, 0
	ds_read_b64_tr_b16 v[76:77], v111 offset:704
	ds_read_b64_tr_b16 v[80:81], v111 offset:736
	ds_read_b64_tr_b16 v[82:83], v112 offset:40960
	ds_read_b64_tr_b16 v[84:85], v112 offset:41600
	ds_read_b64_tr_b16 v[86:87], v113
	ds_read_b64_tr_b16 v[90:91], v113 offset:32
	ds_read_b64_tr_b16 v[94:95], v113 offset:64
	ds_read_b64_tr_b16 v[98:99], v113 offset:96
	ds_read_b64_tr_b16 v[88:89], v113 offset:640
	ds_read_b64_tr_b16 v[92:93], v113 offset:672
	ds_read_b64_tr_b16 v[96:97], v113 offset:704
	ds_read_b64_tr_b16 v[100:101], v113 offset:736
	s_mul_i32 s8, s10, 34
	v_lshlrev_b32_e32 v34, 10, v34
	s_waitcnt lgkmcnt(14)
	v_mfma_f32_16x16x32_bf16 v[20:23], v[16:19], v[20:23], 0
	v_readlane_b32 s9, v254, 40
	s_add_i32 s0, s0, s8
	s_lshl_b32 s0, s0, 13
	v_mfma_f32_16x16x32_bf16 v[24:27], v[16:19], v[24:27], 0
	v_add3_u32 v34, s9, v34, v102
	v_add_u32_e32 v34, 0xf000, v34
	v_readlane_b32 s19, v254, 54
	v_mfma_f32_16x16x32_bf16 v[28:31], v[16:19], v[28:31], 0
	s_add_i32 s0, s0, s19
	v_readlane_b32 s20, v254, 19
	v_readlane_b32 s21, v254, 20
	v_mfma_f32_16x16x32_bf16 v[16:19], v[16:19], v[38:41], 0
	v_readlane_b32 s22, v254, 21
	v_readlane_b32 s23, v254, 22
	v_mfma_f32_16x16x32_bf16 v[20:23], v[42:45], v[46:49], v[20:23]
	v_mfma_f32_16x16x32_bf16 v[24:27], v[42:45], v[50:53], v[24:27]
	v_mfma_f32_16x16x32_bf16 v[28:31], v[42:45], v[54:57], v[28:31]
	v_mfma_f32_16x16x32_bf16 v[16:19], v[42:45], v[58:61], v[16:19]
	v_mfma_f32_16x16x32_bf16 v[20:23], v[62:65], v[66:69], v[20:23]
	v_mfma_f32_16x16x32_bf16 v[24:27], v[62:65], v[70:73], v[24:27]
	s_waitcnt lgkmcnt(11)
	v_mfma_f32_16x16x32_bf16 v[28:31], v[62:65], v[74:77], v[28:31]
	s_waitcnt lgkmcnt(10)
	v_mfma_f32_16x16x32_bf16 v[16:19], v[62:65], v[78:81], v[16:19]
	s_waitcnt lgkmcnt(3)
	v_mfma_f32_16x16x32_bf16 v[20:23], v[82:85], v[86:89], v[20:23]
	v_lshl_add_u32 v87, v207, 4, s9
	v_lshlrev_b32_e32 v86, 2, v207
	v_or_b32_e32 v38, s0, v86
	s_waitcnt lgkmcnt(2)
	v_mfma_f32_16x16x32_bf16 v[24:27], v[82:85], v[90:93], v[24:27]
	v_lshlrev_b32_e32 v38, 2, v38
	s_waitcnt lgkmcnt(1)
	v_mfma_f32_16x16x32_bf16 v[28:31], v[82:85], v[94:97], v[28:31]
	s_waitcnt lgkmcnt(0)
	v_mfma_f32_16x16x32_bf16 v[16:19], v[82:85], v[98:101], v[16:19]
	s_nop 2
	ds_write2_b32 v34, v20, v24 offset1:16
	ds_write2_b32 v34, v21, v25 offset0:64 offset1:80
	ds_write2_b32 v34, v22, v26 offset0:128 offset1:144
	ds_write2_b32 v34, v23, v27 offset0:192 offset1:208
	s_nop 0
	ds_write2_b32 v34, v28, v16 offset0:32 offset1:48
	ds_write2_b32 v34, v29, v17 offset0:96 offset1:112
	ds_write2_b32 v34, v30, v18 offset0:160 offset1:176
	ds_write2_b32 v34, v31, v19 offset0:224 offset1:240
	s_waitcnt lgkmcnt(0)
	ds_read_b128 v[16:19], v87 offset:61440
	ds_read_b128 v[20:23], v87 offset:62464
	ds_read_b128 v[24:27], v87 offset:63488
	ds_read_b128 v[28:31], v87 offset:64512
	s_waitcnt lgkmcnt(3)
	buffer_store_dwordx4 v[16:19], v38, s[20:23], 0 offen sc1
	s_waitcnt lgkmcnt(2)
	buffer_store_dwordx4 v[20:23], v38, s[20:23], 0 offen offset:1024 sc1
	s_waitcnt lgkmcnt(1)
	buffer_store_dwordx4 v[24:27], v38, s[20:23], 0 offen offset:2048 sc1
	s_waitcnt lgkmcnt(0)
	buffer_store_dwordx4 v[28:31], v38, s[20:23], 0 offen offset:3072 sc1
	s_waitcnt vmcnt(7)
	v_lshlrev_b32_e32 v16, 16, v12
	v_and_b32_e32 v18, 0xffff0000, v12
	v_mul_f32_e32 v17, v103, v16
	v_mul_f32_e32 v12, v103, v18
	v_cvt_pk_bf16_f32 v12, v17, v12
	v_lshlrev_b32_e32 v17, 16, v13
	v_and_b32_e32 v20, 0xffff0000, v13
	v_mul_f32_e32 v19, v103, v17
	v_mul_f32_e32 v13, v103, v20
	v_cvt_pk_bf16_f32 v13, v19, v13
	v_lshlrev_b32_e32 v19, 16, v14
	v_and_b32_e32 v22, 0xffff0000, v14
	v_mul_f32_e32 v21, v103, v19
	v_mul_f32_e32 v14, v103, v22
	v_cvt_pk_bf16_f32 v14, v21, v14
	v_lshlrev_b32_e32 v21, 16, v15
	v_and_b32_e32 v24, 0xffff0000, v15
	v_mul_f32_e32 v23, v103, v21
	v_mul_f32_e32 v15, v103, v24
	v_cvt_pk_bf16_f32 v15, v23, v15
	s_waitcnt lgkmcnt(0)
	s_barrier
	ds_write_b128 v105, v[12:15]
	v_mul_f32_e32 v12, v104, v16
	v_mul_f32_e32 v13, v104, v18
	v_cvt_pk_bf16_f32 v12, v12, v13
	v_mul_f32_e32 v13, v104, v17
	v_mul_f32_e32 v14, v104, v20
	v_cvt_pk_bf16_f32 v13, v13, v14
	v_mul_f32_e32 v14, v104, v19
	v_mul_f32_e32 v15, v104, v22
	v_cvt_pk_bf16_f32 v14, v14, v15
	v_mul_f32_e32 v15, v104, v21
	v_mul_f32_e32 v16, v104, v24
	v_cvt_pk_bf16_f32 v15, v15, v16
	ds_write_b128 v105, v[12:15] offset:20480
	s_waitcnt vmcnt(6)
	ds_write_b128 v105, v[8:11] offset:40960
	s_waitcnt vmcnt(5)
	v_lshlrev_b32_e32 v8, 16, v4
	v_and_b32_e32 v10, 0xffff0000, v4
	v_mul_f32_e32 v9, v35, v8
	v_mul_f32_e32 v4, v35, v10
	v_cvt_pk_bf16_f32 v4, v9, v4
	v_lshlrev_b32_e32 v9, 16, v5
	v_and_b32_e32 v12, 0xffff0000, v5
	v_mul_f32_e32 v11, v35, v9
	v_mul_f32_e32 v5, v35, v12
	v_cvt_pk_bf16_f32 v5, v11, v5
	v_lshlrev_b32_e32 v11, 16, v6
	v_and_b32_e32 v14, 0xffff0000, v6
	v_mul_f32_e32 v13, v35, v11
	v_mul_f32_e32 v6, v35, v14
	v_cvt_pk_bf16_f32 v6, v13, v6
	v_lshlrev_b32_e32 v13, 16, v7
	v_and_b32_e32 v16, 0xffff0000, v7
	v_mul_f32_e32 v15, v35, v13
	v_mul_f32_e32 v7, v35, v16
	v_cvt_pk_bf16_f32 v7, v15, v7
	ds_write_b128 v37, v[4:7]
	v_mul_f32_e32 v4, v32, v8
	v_mul_f32_e32 v5, v32, v10
	v_cvt_pk_bf16_f32 v4, v4, v5
	v_mul_f32_e32 v5, v32, v9
	v_mul_f32_e32 v6, v32, v12
	v_cvt_pk_bf16_f32 v5, v5, v6
	v_mul_f32_e32 v6, v32, v11
	v_mul_f32_e32 v7, v32, v14
	v_cvt_pk_bf16_f32 v6, v6, v7
	v_mul_f32_e32 v7, v32, v13
	v_mul_f32_e32 v8, v32, v16
	v_cvt_pk_bf16_f32 v7, v7, v8
	ds_write_b128 v37, v[4:7] offset:20480
	s_waitcnt vmcnt(4)
	ds_write_b128 v37, v[0:3] offset:40960
	s_waitcnt lgkmcnt(0)
	s_barrier
	ds_read_b64_tr_b16 v[0:1], v106 offset:40960
	ds_read_b64_tr_b16 v[2:3], v106 offset:41600
	ds_read_b64_tr_b16 v[4:5], v107
	ds_read_b64_tr_b16 v[8:9], v107 offset:32
	ds_read_b64_tr_b16 v[6:7], v107 offset:640
	ds_read_b64_tr_b16 v[10:11], v107 offset:672
	ds_read_b64_tr_b16 v[12:13], v107 offset:64
	ds_read_b64_tr_b16 v[16:17], v107 offset:96
	ds_read_b64_tr_b16 v[14:15], v107 offset:704
	ds_read_b64_tr_b16 v[18:19], v107 offset:736
	ds_read_b64_tr_b16 v[20:21], v108 offset:40960
	ds_read_b64_tr_b16 v[22:23], v108 offset:41600
	ds_read_b64_tr_b16 v[24:25], v109
	ds_read_b64_tr_b16 v[28:29], v109 offset:32
	ds_read_b64_tr_b16 v[38:39], v109 offset:64
	ds_read_b64_tr_b16 v[42:43], v109 offset:96
	ds_read_b64_tr_b16 v[26:27], v109 offset:640
	ds_read_b64_tr_b16 v[30:31], v109 offset:672
	ds_read_b64_tr_b16 v[40:41], v109 offset:704
	ds_read_b64_tr_b16 v[44:45], v109 offset:736
	ds_read_b64_tr_b16 v[46:47], v110 offset:40960
	ds_read_b64_tr_b16 v[48:49], v110 offset:41600
	ds_read_b64_tr_b16 v[50:51], v111
	ds_read_b64_tr_b16 v[54:55], v111 offset:32
	ds_read_b64_tr_b16 v[52:53], v111 offset:640
	ds_read_b64_tr_b16 v[56:57], v111 offset:672
	ds_read_b64_tr_b16 v[58:59], v111 offset:64
	ds_read_b64_tr_b16 v[62:63], v111 offset:96
	ds_read_b64_tr_b16 v[60:61], v111 offset:704
	ds_read_b64_tr_b16 v[64:65], v111 offset:736
	ds_read_b64_tr_b16 v[66:67], v112 offset:40960
	ds_read_b64_tr_b16 v[68:69], v112 offset:41600
	ds_read_b64_tr_b16 v[70:71], v113
	ds_read_b64_tr_b16 v[74:75], v113 offset:32
	ds_read_b64_tr_b16 v[78:79], v113 offset:64
	ds_read_b64_tr_b16 v[82:83], v113 offset:96
	ds_read_b64_tr_b16 v[72:73], v113 offset:640
	ds_read_b64_tr_b16 v[76:77], v113 offset:672
	ds_read_b64_tr_b16 v[80:81], v113 offset:704
	ds_read_b64_tr_b16 v[84:85], v113 offset:736
	s_waitcnt lgkmcnt(14)
	v_mfma_f32_16x16x32_bf16 v[4:7], v[0:3], v[4:7], 0
	s_add_i32 s17, s17, s8
	s_lshl_b32 s0, s17, 13
	s_add_i32 s0, s0, s19
	v_mfma_f32_16x16x32_bf16 v[8:11], v[0:3], v[8:11], 0
	s_and_b32 s8, s10, 0x7fffffc
	s_mov_b32 s95, s12
	v_mfma_f32_16x16x32_bf16 v[12:15], v[0:3], v[12:15], 0
	v_mfma_f32_16x16x32_bf16 v[0:3], v[0:3], v[16:19], 0
	v_or_b32_e32 v16, s0, v86
	s_lshl_b32 s0, s5, 4
	s_add_i32 s0, s0, s8
	v_mfma_f32_16x16x32_bf16 v[4:7], v[20:23], v[24:27], v[4:7]
	s_or_b32 s0, s0, s11
	v_lshlrev_b32_e32 v16, 2, v16
	s_lshl_b32 s8, s0, 4
	v_mfma_f32_16x16x32_bf16 v[8:11], v[20:23], v[28:31], v[8:11]
	s_ashr_i32 s9, s8, 31
	s_lshl_b64 s[8:9], s[8:9], 2
	v_readlane_b32 s0, v254, 59
	v_mfma_f32_16x16x32_bf16 v[12:15], v[20:23], v[38:41], v[12:15]
	s_add_u32 s76, s0, s8
	v_readlane_b32 s0, v254, 60
	s_addc_u32 s77, s0, s9
	v_mfma_f32_16x16x32_bf16 v[0:3], v[20:23], v[42:45], v[0:3]
	s_mov_b64 s[10:11], 0
	v_mfma_f32_16x16x32_bf16 v[4:7], v[46:49], v[50:53], v[4:7]
	v_mfma_f32_16x16x32_bf16 v[8:11], v[46:49], v[54:57], v[8:11]
	s_waitcnt lgkmcnt(11)
	v_mfma_f32_16x16x32_bf16 v[12:15], v[46:49], v[58:61], v[12:15]
	s_waitcnt lgkmcnt(10)
	v_mfma_f32_16x16x32_bf16 v[0:3], v[46:49], v[62:65], v[0:3]
	s_waitcnt lgkmcnt(3)
	v_mfma_f32_16x16x32_bf16 v[4:7], v[66:69], v[70:73], v[4:7]
	s_waitcnt lgkmcnt(2)
	v_mfma_f32_16x16x32_bf16 v[8:11], v[66:69], v[74:77], v[8:11]
	s_waitcnt lgkmcnt(1)
	v_mfma_f32_16x16x32_bf16 v[12:15], v[66:69], v[78:81], v[12:15]
	s_waitcnt lgkmcnt(0)
	v_mfma_f32_16x16x32_bf16 v[0:3], v[66:69], v[82:85], v[0:3]
	s_nop 3
	ds_write2_b32 v34, v4, v8 offset1:16
	ds_write2_b32 v34, v5, v9 offset0:64 offset1:80
	ds_write2_b32 v34, v6, v10 offset0:128 offset1:144
	ds_write2_b32 v34, v7, v11 offset0:192 offset1:208
	ds_write2_b32 v34, v12, v0 offset0:32 offset1:48
	ds_write2_b32 v34, v13, v1 offset0:96 offset1:112
	ds_write2_b32 v34, v14, v2 offset0:160 offset1:176
	ds_write2_b32 v34, v15, v3 offset0:224 offset1:240
	s_waitcnt lgkmcnt(0)
	ds_read_b128 v[0:3], v87 offset:61440
	ds_read_b128 v[4:7], v87 offset:62464
	ds_read_b128 v[8:11], v87 offset:63488
	ds_read_b128 v[12:15], v87 offset:64512
	s_waitcnt lgkmcnt(3)
	buffer_store_dwordx4 v[0:3], v16, s[20:23], 0 offen sc1
	s_waitcnt lgkmcnt(2)
	buffer_store_dwordx4 v[4:7], v16, s[20:23], 0 offen offset:1024 sc1
	s_waitcnt lgkmcnt(1)
	buffer_store_dwordx4 v[8:11], v16, s[20:23], 0 offen offset:2048 sc1
	s_waitcnt lgkmcnt(0)
	buffer_store_dwordx4 v[12:15], v16, s[20:23], 0 offen offset:3072 sc1
	s_waitcnt lgkmcnt(0)

.LBB0_726:
	s_or_b64 exec, exec, s[12:13]
	s_bfe_u32 s0, s9, 0x10001
	s_mulk_i32 s8, 0x44
	s_or_b32 s8, s8, s0
	s_lshl_b32 s92, s8, 12
	s_lshl_b64 s[12:13], s[92:93], 2
	v_readlane_b32 s16, v254, 19
	v_readlane_b32 s17, v254, 20
	s_add_u32 s16, s16, s12
	v_readlane_b32 s12, v254, 58
	v_readlane_b32 s18, v254, 21
	s_addc_u32 s17, s12, s13
	s_lshl_b32 s8, s8, 13
	v_readlane_b32 s12, v254, 61
	v_readlane_b32 s19, v254, 22
	v_readlane_b32 s13, v254, 62
	s_add_u32 s18, s12, s8
	s_addc_u32 s19, s13, 0
	s_lshl_b32 s12, s5, 3
	s_lshl_b32 s13, s0, 2
	s_bfe_u32 s8, s9, 0x20002
	s_or_b32 s12, s13, s12
	s_or_b32 s12, s12, s8
	s_ashr_i32 s13, s12, 31
	s_lshl_b64 s[12:13], s[12:13], 2
	s_add_u32 s12, s42, s12
	s_addc_u32 s13, s43, s13
	s_barrier
	s_load_dword s100, s[12:13], 0x0
	s_mov_b32 s8, 0xbfb8aa3b
	s_mov_b32 s12, 0x3f317218
	s_lshl_b32 s9, s9, 5
	s_and_b32 s9, s9, 32
	v_mov_b32_e32 v80, 0
	s_cmp_eq_u32 s0, 0
	v_mov_b32_e32 v81, v80
	v_mov_b32_e32 v82, v80
	v_mov_b32_e32 v83, v80
	s_waitcnt lgkmcnt(0)
	v_mov_b32_e32 v0, s100
	v_mul_f32_e32 v1, 0xbfb8aa3b, v0
	v_fma_f32 v2, v0, s8, -v1
	v_rndne_f32_e32 v3, v1
	v_fmac_f32_e32 v2, 0xb2a5705f, v0
	v_sub_f32_e32 v1, v1, v3
	v_add_f32_e32 v1, v1, v2
	v_exp_f32_e32 v1, v1
	v_cvt_i32_f32_e32 v2, v3
	s_mov_b32 s8, 0x42ce8ed0
	v_cmp_nlt_f32_e32 vcc, s8, v0
	s_mov_b32 s8, 0xc2b17218
	v_ldexp_f32 v1, v1, v2
	v_cndmask_b32_e32 v1, 0, v1, vcc
	v_cmp_ngt_f32_e32 vcc, s8, v0
	s_mov_b32 s8, 0x3f2aaaab
	s_nop 0
	v_cndmask_b32_e32 v16, v227, v1, vcc
	v_add_f32_e32 v2, 1.0, v16
	v_add_f32_e32 v0, -1.0, v2
	v_sub_f32_e32 v1, v0, v2
	v_add_f32_e32 v1, 1.0, v1
	v_sub_f32_e32 v0, v16, v0
	v_add_f32_e32 v3, v0, v1
	v_frexp_mant_f32_e32 v0, v2
	v_cmp_gt_f32_e32 vcc, s8, v0
	v_cvt_f64_f32_e32 v[0:1], v2
	v_frexp_exp_i32_f64_e32 v0, v[0:1]
	v_subbrev_co_u32_e32 v8, vcc, 0, v0, vcc
	v_sub_u32_e32 v0, 0, v8
	v_ldexp_f32 v1, v2, v0
	v_add_f32_e32 v2, -1.0, v1
	v_add_f32_e32 v4, 1.0, v1
	v_ldexp_f32 v0, v3, v0
	v_add_f32_e32 v3, 1.0, v2
	v_add_f32_e32 v5, -1.0, v4
	v_sub_f32_e32 v3, v1, v3
	v_sub_f32_e32 v1, v1, v5
	v_add_f32_e32 v3, v0, v3
	v_add_f32_e32 v0, v0, v1
	v_add_f32_e32 v9, v4, v0
	v_rcp_f32_e32 v11, v9
	v_sub_f32_e32 v1, v4, v9
	v_add_f32_e32 v10, v0, v1
	v_add_f32_e32 v1, v2, v3
	v_mul_f32_e32 v13, v1, v11
	v_sub_f32_e32 v0, v2, v1
	v_mul_f32_e32 v2, v9, v13
	v_fma_f32 v4, v13, v9, -v2
	v_fmac_f32_e32 v4, v13, v10
	v_add_f32_e32 v12, v3, v0
	v_add_f32_e32 v0, v2, v4
	v_sub_f32_e32 v3, v1, v0
	v_pk_add_f32 v[6:7], v[0:1], v[2:3] neg_lo:[0,1] neg_hi:[0,1]
	v_mov_b32_e32 v5, v0
	v_pk_add_f32 v[0:1], v[6:7], v[4:5] neg_lo:[0,1] neg_hi:[0,1]
	s_mov_b32 s8, 0
	v_add_f32_e32 v1, v12, v1
	v_add_f32_e32 v0, v0, v1
	v_add_f32_e32 v1, v3, v0
	v_mul_f32_e32 v12, v11, v1
	v_mul_f32_e32 v2, v9, v12
	v_fma_f32 v4, v12, v9, -v2
	v_fmac_f32_e32 v4, v12, v10
	v_sub_f32_e32 v3, v3, v1
	v_add_f32_e32 v9, v0, v3
	v_add_f32_e32 v0, v2, v4
	v_sub_f32_e32 v3, v1, v0
	v_pk_add_f32 v[6:7], v[0:1], v[2:3] neg_lo:[0,1] neg_hi:[0,1]
	v_mov_b32_e32 v5, v0
	v_pk_add_f32 v[0:1], v[6:7], v[4:5] neg_lo:[0,1] neg_hi:[0,1]
	s_nop 0
	v_add_f32_e32 v1, v9, v1
	v_add_f32_e32 v0, v0, v1
	v_add_f32_e32 v1, v13, v12
	v_add_f32_e32 v0, v3, v0
	v_sub_f32_e32 v2, v1, v13
	v_mul_f32_e32 v0, v11, v0
	v_sub_f32_e32 v2, v12, v2
	v_add_f32_e32 v2, v2, v0
	v_add_f32_e32 v4, v1, v2
	v_mul_f32_e32 v5, v4, v4
	v_fmamk_f32 v0, v5, 0x3e9b6dac, v252
	v_fmaak_f32 v201, v5, v0, 0x3f2aaada
	v_cvt_f32_i32_e32 v0, v8
	v_sub_f32_e32 v1, v4, v1
	v_sub_f32_e32 v1, v2, v1
	v_ldexp_f32 v6, v1, 1
	v_mul_f32_e32 v1, v4, v5
	v_ldexp_f32 v3, v4, 1
	v_pk_mul_f32 v[4:5], v[0:1], v[200:201]
	s_nop 0
	v_fma_f32 v2, v0, s12, -v4
	v_fmac_f32_e32 v2, 0xb102e308, v0
	v_pk_add_f32 v[0:1], v[4:5], v[2:3]
	s_mov_b32 s12, 0x7f800000
	v_sub_f32_e32 v3, v1, v3
	v_sub_f32_e32 v3, v5, v3
	v_add_f32_e32 v7, v6, v3
	v_mov_b32_e32 v6, v4
	v_pk_add_f32 v[4:5], v[0:1], v[4:5] neg_lo:[0,1] neg_hi:[0,1]
	v_pk_add_f32 v[8:9], v[0:1], v[6:7]
	v_mov_b32_e32 v3, v0
	v_mov_b32_e32 v5, v9
	v_pk_add_f32 v[10:11], v[2:3], v[4:5] neg_lo:[0,1] neg_hi:[0,1]
	v_pk_add_f32 v[2:3], v[2:3], v[4:5]
	v_mov_b32_e32 v14, v1
	v_pk_add_f32 v[4:5], v[2:3], v[0:1] op_sel:[1,0] op_sel_hi:[0,1] neg_lo:[0,1] neg_hi:[0,1]
	v_pk_add_f32 v[12:13], v[8:9], v[4:5] op_sel_hi:[1,0] neg_lo:[0,1] neg_hi:[0,1]
	v_mov_b32_e32 v8, v9
	v_mov_b32_e32 v9, v3
	v_mov_b32_e32 v15, v4
	v_pk_add_f32 v[4:5], v[8:9], v[14:15] neg_lo:[0,1] neg_hi:[0,1]
	v_mov_b32_e32 v6, v7
	v_mov_b32_e32 v7, v0
	v_pk_add_f32 v[0:1], v[6:7], v[4:5] neg_lo:[0,1] neg_hi:[0,1]
	v_mov_b32_e32 v12, v10
	v_pk_add_f32 v[4:5], v[12:13], v[0:1]
	v_mov_b32_e32 v11, v3
	v_pk_add_f32 v[6:7], v[4:5], v[4:5] op_sel:[0,1] op_sel_hi:[1,0]
	v_cmp_neq_f32_e32 vcc, s12, v16
	v_pk_add_f32 v[2:3], v[2:3], v[6:7] op_sel:[1,0] op_sel_hi:[0,1]
	v_mov_b32_e32 v5, v2
	v_pk_add_f32 v[8:9], v[4:5], v[10:11] neg_lo:[0,1] neg_hi:[0,1]
	v_mov_b32_e32 v1, v6
	v_sub_f32_e32 v3, v4, v8
	v_pk_add_f32 v[0:1], v[0:1], v[8:9] neg_lo:[0,1] neg_hi:[0,1]
	v_sub_f32_e32 v3, v10, v3
	v_add_f32_e32 v0, v0, v3
	v_add_f32_e32 v0, v0, v1
	v_add_f32_e32 v0, v2, v0
	s_mov_b32 s12, 0x33800000
	v_cndmask_b32_e32 v0, v227, v0, vcc
	v_cmp_lt_f32_e64 vcc, |v16|, s12
	v_lshlrev_b32_e32 v1, 2, v206
	v_and_b32_e32 v1, 60, v1
	v_cndmask_b32_e32 v0, v0, v16, vcc
	v_mul_f32_e32 v0, 0xbfb8aa3b, v0
	v_mul_f32_e32 v0, 0x43000000, v0
	v_exp_f32_e32 v34, v0
	v_lshrrev_b32_e32 v0, 4, v206
	v_add_u32_e32 v0, s9, v0
	v_lshl_or_b32 v0, v0, 6, v1
	v_ashrrev_i32_e32 v1, 31, v0
	s_cselect_b64 s[12:13], -1, 0
	v_lshl_add_u64 v[74:75], v[0:1], 2, s[16:17]
	v_lshl_add_u64 v[76:77], v[0:1], 1, s[18:19]
	v_mov_b32_e32 v78, v34
	v_mov_b32_e32 v79, v34
	s_mov_b32 s9, 19
